# conv tables pre-scaled (c for silu-half cols, 1/c for gate-half cols) in phase 1; GEMM4 epilogue drops the per-element exp2 scale multiply
# baseline (speedup 1.0000x reference)
.LBB0_581:
	s_or_b64 exec, exec, s[40:41]
	s_waitcnt vmcnt(0)
	v_fmac_f32_e32 v72, v67, v73
	v_mul_f32_e32 v72, v72, v120
	global_store_dword v[68:69], v72, off

.LBB0_583:
	v_and_b32_e32 v120, 0x80, v66
	v_mov_b32_e32 v121, 0xbf317218
	v_mov_b32_e32 v122, 0xbfb8aa3b
	v_cmp_eq_u32_e64 s[40:41], 0, v120
	s_nop 1
	v_cndmask_b32_e64 v120, v121, v122, s[40:41]
	s_waitcnt lgkmcnt(2)
	global_load_dwordx4 v[82:85], v[70:71], off
	s_waitcnt lgkmcnt(1)
	global_load_dwordx4 v[86:89], v[70:71], off offset:1024
	s_waitcnt vmcnt(2)
	v_bfe_i32 v67, v66, 7, 1
	v_ashrrev_i32_e32 v72, 1, v66
	v_and_b32_e32 v67, 0xb00, v67
	v_and_b32_e32 v72, 0xffffff80, v72
	v_add_u32_e32 v67, v67, v72
	v_and_or_b32 v72, v66, s35, v67
	s_waitcnt vmcnt(1)
	v_and_b32_e32 v73, 0xffff0000, v82
	v_lshlrev_b32_e32 v67, 16, v82
	v_lshlrev_b32_e32 v81, 16, v83
	v_and_b32_e32 v82, 0xffff0000, v83
	v_lshlrev_b32_e32 v83, 16, v84
	v_and_b32_e32 v84, 0xffff0000, v84
	s_waitcnt vmcnt(0)
	v_lshlrev_b32_e32 v92, 16, v87
	v_and_b32_e32 v93, 0xffff0000, v87
	s_waitcnt lgkmcnt(14)
	v_mul_f32_e32 v87, v3, v73
	s_waitcnt lgkmcnt(13)
	v_mul_f32_e32 v94, v11, v73
	s_waitcnt lgkmcnt(11)
	v_mul_f32_e32 v95, v19, v73
	s_waitcnt lgkmcnt(9)
	v_mul_f32_e32 v73, v27, v73
	v_mul_f32_e32 v96, v5, v82
	v_mul_f32_e32 v97, v13, v82
	v_mul_f32_e32 v98, v21, v82
	v_mul_f32_e32 v82, v29, v82
	v_mul_f32_e32 v99, v7, v84
	v_mul_f32_e32 v100, v15, v84
	v_mul_f32_e32 v101, v23, v84
	s_waitcnt lgkmcnt(8)
	v_mul_f32_e32 v84, v31, v84
	v_fmac_f32_e32 v95, v18, v67
	v_fmac_f32_e32 v73, v26, v67
	s_waitcnt lgkmcnt(0)
	v_lshlrev_b32_e32 v90, 16, v85
	v_and_b32_e32 v85, 0xffff0000, v85
	v_fmac_f32_e32 v98, v20, v81
	v_fmac_f32_e32 v82, v28, v81
	v_fmac_f32_e32 v99, v6, v83
	v_fmac_f32_e32 v100, v14, v83
	v_fmac_f32_e32 v101, v22, v83
	v_fmac_f32_e32 v84, v30, v83
	v_add_f32_e32 v83, 0, v95
	v_add_f32_e32 v73, 0, v73
	v_lshlrev_b32_e32 v91, 16, v86
	v_and_b32_e32 v86, 0xffff0000, v86
	v_mul_f32_e32 v102, v9, v85
	v_mul_f32_e32 v103, v17, v85
	v_mul_f32_e32 v104, v25, v85
	v_mul_f32_e32 v85, v33, v85
	v_add_f32_e32 v83, v83, v98
	v_add_f32_e32 v73, v73, v82
	s_waitcnt lgkmcnt(7)
	v_mul_f32_e32 v105, v35, v86
	s_waitcnt lgkmcnt(5)
	v_mul_f32_e32 v106, v43, v86
	s_waitcnt lgkmcnt(3)
	v_mul_f32_e32 v107, v51, v86
	s_waitcnt lgkmcnt(1)
	v_mul_f32_e32 v86, v59, v86
	v_fmac_f32_e32 v104, v24, v90
	v_fmac_f32_e32 v85, v32, v90
	v_add_f32_e32 v82, v83, v101
	v_add_f32_e32 v73, v73, v84
	v_mul_f32_e32 v110, v53, v93
	v_fmac_f32_e32 v87, v2, v67
	v_fmac_f32_e32 v94, v10, v67
	v_fmac_f32_e32 v107, v50, v91
	v_fmac_f32_e32 v86, v58, v91
	v_add_f32_e32 v82, v82, v104
	v_add_f32_e32 v73, v73, v85
	v_fmac_f32_e32 v96, v4, v81
	v_fmac_f32_e32 v97, v12, v81
	v_fmac_f32_e32 v102, v8, v90
	v_fmac_f32_e32 v103, v16, v90
	v_fmac_f32_e32 v110, v52, v92
	v_add_f32_e32 v67, 0, v87
	v_add_f32_e32 v81, 0, v94
	v_add_f32_e32 v82, v82, v107
	v_add_f32_e32 v90, v73, v86
	v_ashrrev_i32_e32 v73, 31, v72
	v_add_f32_e32 v67, v67, v96
	v_add_f32_e32 v81, v81, v97
	v_add_f32_e32 v95, v82, v110
	v_lshl_add_u64 v[82:83], v[72:73], 2, s[76:77]
	v_add_f32_e32 v67, v67, v99
	v_add_f32_e32 v81, v81, v100
	v_add_co_u32_e32 v84, vcc, 0x5000, v82
	v_mul_f32_e32 v108, v37, v93
	v_mul_f32_e32 v109, v45, v93
	v_fmac_f32_e32 v105, v34, v91
	v_fmac_f32_e32 v106, v42, v91
	v_add_f32_e32 v67, v67, v102
	v_add_f32_e32 v81, v81, v103
	v_addc_co_u32_e32 v85, vcc, 0, v83, vcc
	v_fmac_f32_e32 v108, v36, v92
	v_fmac_f32_e32 v109, v44, v92
	v_add_f32_e32 v67, v67, v105
	v_add_f32_e32 v81, v81, v106
	v_add_co_u32_e32 v86, vcc, 0xb000, v82
	v_add_f32_e32 v91, v67, v108
	v_add_f32_e32 v94, v81, v109
	v_addc_co_u32_e32 v87, vcc, 0, v83, vcc
	global_load_dword v82, v[82:83], off
	s_nop 0
	global_load_dword v81, v[84:85], off offset:2048
	global_load_dword v67, v[86:87], off
	v_and_b32_e32 v85, 0xffff0000, v88
	v_lshlrev_b32_e32 v84, 16, v88
	v_mul_f32_e32 v86, v39, v85
	v_and_b32_e32 v88, 0xffff0000, v89
	v_fmac_f32_e32 v86, v38, v84
	v_lshlrev_b32_e32 v87, 16, v89
	v_mul_f32_e32 v89, v41, v88
	v_add_f32_e32 v86, v91, v86
	v_fmac_f32_e32 v89, v40, v87
	v_add_f32_e32 v86, v86, v89
	ds_bpermute_b32 v89, v1, v86
	v_mul_f32_e32 v83, v61, v93
	v_fmac_f32_e32 v83, v60, v92
	v_add_f32_e32 v83, v90, v83
	v_mul_f32_e32 v90, v47, v85
	s_waitcnt lgkmcnt(0)
	v_add_f32_e32 v86, v86, v89
	ds_bpermute_b32 v89, v74, v86
	v_mul_f32_e32 v91, v55, v85
	v_mul_f32_e32 v85, v63, v85
	v_fmac_f32_e32 v85, v62, v84
	v_add_f32_e32 v83, v83, v85
	s_waitcnt lgkmcnt(0)
	v_add_f32_e32 v86, v86, v89
	ds_bpermute_b32 v89, v75, v86
	v_fmac_f32_e32 v90, v46, v84
	v_fmac_f32_e32 v91, v54, v84
	v_mul_f32_e32 v84, v49, v88
	v_add_f32_e32 v90, v94, v90
	s_waitcnt lgkmcnt(0)
	v_add_f32_e32 v85, v86, v89
	ds_bpermute_b32 v86, v76, v85
	v_fmac_f32_e32 v84, v48, v87
	v_add_f32_e32 v89, v90, v84
	v_mul_f32_e32 v84, v57, v88
	v_add_f32_e32 v91, v95, v91
	v_fmac_f32_e32 v84, v56, v87
	v_add_f32_e32 v90, v91, v84
	s_waitcnt lgkmcnt(0)
	v_add_f32_e32 v84, v85, v86
	ds_bpermute_b32 v85, v77, v84
	v_mul_f32_e32 v86, v65, v88
	v_fmac_f32_e32 v86, v64, v87
	v_add_f32_e32 v83, v83, v86
	ds_bpermute_b32 v87, v1, v89
	s_waitcnt lgkmcnt(1)
	v_add_f32_e32 v84, v84, v85
	ds_bpermute_b32 v85, v1, v90
	ds_bpermute_b32 v88, v1, v83
	ds_bpermute_b32 v86, v78, v84
	s_waitcnt lgkmcnt(3)
	v_add_f32_e32 v87, v89, v87
	ds_bpermute_b32 v89, v74, v87
	s_waitcnt lgkmcnt(3)
	v_add_f32_e32 v85, v90, v85
	s_waitcnt lgkmcnt(2)
	v_add_f32_e32 v83, v83, v88
	ds_bpermute_b32 v90, v74, v85
	ds_bpermute_b32 v88, v74, v83
	s_waitcnt lgkmcnt(2)
	v_add_f32_e32 v87, v87, v89
	ds_bpermute_b32 v89, v75, v87
	s_waitcnt lgkmcnt(2)
	v_add_f32_e32 v85, v85, v90
	s_waitcnt lgkmcnt(1)
	v_add_f32_e32 v83, v83, v88
	ds_bpermute_b32 v90, v75, v85
	ds_bpermute_b32 v88, v75, v83
	s_waitcnt lgkmcnt(2)
	v_add_f32_e32 v87, v87, v89
	ds_bpermute_b32 v89, v76, v87
	s_waitcnt lgkmcnt(2)
	v_add_f32_e32 v85, v85, v90
	s_waitcnt lgkmcnt(1)
	v_add_f32_e32 v83, v83, v88
	ds_bpermute_b32 v90, v76, v85
	ds_bpermute_b32 v88, v76, v83
	s_waitcnt lgkmcnt(2)
	v_add_f32_e32 v87, v87, v89
	ds_bpermute_b32 v89, v77, v87
	s_waitcnt lgkmcnt(2)
	v_add_f32_e32 v90, v85, v90
	s_waitcnt lgkmcnt(1)
	v_add_f32_e32 v92, v83, v88
	ds_bpermute_b32 v91, v77, v90
	ds_bpermute_b32 v93, v77, v92
	s_waitcnt lgkmcnt(2)
	v_add_f32_e32 v83, v87, v89
	ds_bpermute_b32 v85, v78, v83
	s_waitcnt lgkmcnt(2)
	v_add_f32_e32 v87, v90, v91
	s_waitcnt lgkmcnt(1)
	v_add_f32_e32 v89, v92, v93
	ds_bpermute_b32 v88, v78, v87
	ds_bpermute_b32 v90, v78, v89
	s_and_saveexec_b64 s[38:39], s[26:27]
	s_xor_b64 s[38:39], exec, s[38:39]
	s_cbranch_execz .LBB0_587
	s_and_saveexec_b64 s[40:41], s[4:5]
	s_cbranch_execz .LBB0_586
	v_add_u32_e32 v72, v79, v66
	v_ashrrev_i32_e32 v73, 31, v72
	s_waitcnt vmcnt(0)
	v_cndmask_b32_e64 v67, v67, v81, s[8:9]
	v_lshl_add_u64 v[72:73], v[72:73], 2, s[20:21]
	v_cndmask_b32_e64 v67, v67, v82, s[6:7]
	v_mul_f32_e32 v67, v67, v120
	global_store_dword v[72:73], v67, off

.LBB0_1198:
	ds_read_b32 v110, v223
	s_waitcnt lgkmcnt(0)
	v_mov_b32_dpp v72, v58 row_shr:1 row_mask:0xf bank_mask:0xf
	v_mov_b32_dpp v73, v59 row_shr:1 row_mask:0xf bank_mask:0xf
	v_mov_b32_dpp v76, v50 row_shr:1 row_mask:0xf bank_mask:0xf
	v_mov_b32_dpp v77, v51 row_shr:1 row_mask:0xf bank_mask:0xf
	v_and_b32_e32 v70, 15, v110
	v_lshl_add_u32 v249, v70, 10, v248
	v_lshlrev_b32_e32 v146, 2, v70
	v_lshl_add_u64 v[70:71], s[68:69], 0, v[146:147]
	v_lshl_add_u64 v[88:89], v[70:71], 0, v[114:115]
	v_and_b32_e32 v71, 16, v110
	v_cmp_eq_u32_e32 vcc, 0, v71
	v_and_b32_e32 v71, 32, v110
	ds_read_b128 v[110:113], v249
	ds_read_b128 v[252:255], v249 offset:512
	v_cmp_eq_u32_e64 s[0:1], 0, v71
	v_cndmask_b32_e64 v116, v66, 0, vcc
	v_cndmask_b32_e64 v117, v67, 0, vcc
	v_cndmask_b32_e64 v118, v68, 0, vcc
	v_cndmask_b32_e64 v119, v69, 0, vcc
	v_cndmask_b32_e64 v84, v84, 0, s[0:1]
	v_cndmask_b32_e64 v85, v85, 0, s[0:1]
	v_cndmask_b32_e64 v86, v86, 0, s[0:1]
	v_cndmask_b32_e64 v87, v87, 0, s[0:1]
	v_cndmask_b32_e64 v76, v76, 0, s[0:1]
	v_cndmask_b32_e64 v77, v77, 0, s[0:1]
	v_mov_b32_dpp v74, v60 row_shr:1 row_mask:0xf bank_mask:0xf
	v_mov_b32_dpp v75, v61 row_shr:1 row_mask:0xf bank_mask:0xf
	v_mov_b32_dpp v78, v52 row_shr:1 row_mask:0xf bank_mask:0xf
	v_mov_b32_dpp v79, v53 row_shr:1 row_mask:0xf bank_mask:0xf
	v_cndmask_b32_e64 v78, v78, 0, s[0:1]
	v_cndmask_b32_e64 v79, v79, 0, s[0:1]
	v_mov_b32_e32 v70, 0
	s_waitcnt vmcnt(0) lgkmcnt(0)
	v_pk_fma_f32 v[112:113], v[212:213], v[108:109], v[112:113]
	v_pk_fma_f32 v[110:111], v[210:211], v[106:107], v[110:111]
	v_pk_fma_f32 v[112:113], v[104:105], v[118:119], v[112:113]
	v_pk_fma_f32 v[110:111], v[102:103], v[116:117], v[110:111]
	v_pk_fma_f32 v[112:113], v[100:101], v[86:87], v[112:113]
	v_pk_fma_f32 v[110:111], v[98:99], v[84:85], v[110:111]
	v_mov_b64_e32 v[84:85], v[252:253]
	v_mov_b64_e32 v[86:87], v[254:255]
	v_exp_f32_e32 v71, v110
	v_cndmask_b32_e64 v88, v72, 0, vcc
	v_cndmask_b32_e64 v89, v73, 0, vcc
	v_cndmask_b32_e64 v116, v74, 0, vcc
	v_add_f32_e32 v71, 1.0, v71
	v_rcp_f32_e32 v71, v71
	v_cndmask_b32_e64 v117, v75, 0, vcc
	v_mul_f32_e32 v71, v110, v71
	s_nop 0
	v_pk_fma_f32 v[84:85], v[214:215], v[94:95], v[84:85]
	s_nop 0
	v_pk_fma_f32 v[84:85], v[90:91], v[88:89], v[84:85]
	v_pk_fma_f32 v[86:87], v[216:217], v[96:97], v[86:87]
	v_pk_fma_f32 v[76:77], v[80:81], v[76:77], v[84:85]
	v_pk_fma_f32 v[86:87], v[92:93], v[116:117], v[86:87]
	v_mul_f32_e32 v71, v76, v71
	v_exp_f32_e32 v76, v111
	v_pk_fma_f32 v[78:79], v[82:83], v[78:79], v[86:87]
	v_add_f32_e32 v76, 1.0, v76
	v_rcp_f32_e32 v76, v76
	s_nop 0
	v_mul_f32_e32 v76, v111, v76
	v_mul_f32_e32 v76, v77, v76
	v_exp_f32_e32 v77, v112
	v_cvt_pk_bf16_f32 v84, v71, v76
	ds_read_b32 v71, v225
	v_add_f32_e32 v77, 1.0, v77
	v_rcp_f32_e32 v77, v77
	s_waitcnt lgkmcnt(0)
	v_and_b32_e32 v76, 15, v71
	v_lshl_add_u32 v249, v76, 10, v248
	v_mul_f32_e32 v77, v112, v77
	v_mul_f32_e32 v77, v78, v77
	v_exp_f32_e32 v78, v113
	v_lshlrev_b32_e32 v146, 2, v76
	v_add_f32_e32 v78, 1.0, v78
	v_rcp_f32_e32 v78, v78
	s_nop 0
	v_mul_f32_e32 v78, v113, v78
	v_mul_f32_e32 v78, v79, v78
	v_cvt_pk_bf16_f32 v85, v77, v78
	v_lshl_add_u64 v[76:77], s[68:69], 0, v[146:147]
	v_lshl_add_u64 v[86:87], v[76:77], 0, v[114:115]
	v_and_b32_e32 v76, 16, v71
	v_cmp_eq_u32_e32 vcc, 0, v76
	ds_read_b128 v[76:79], v249
	ds_read_b128 v[252:255], v249 offset:512
	v_and_b32_e32 v71, 32, v71
	v_cmp_eq_u32_e64 s[0:1], 0, v71
	v_cndmask_b32_e64 v88, v210, 0, vcc
	v_cndmask_b32_e64 v89, v211, 0, vcc
	v_cndmask_b32_e64 v110, v212, 0, vcc
	v_cndmask_b32_e64 v111, v213, 0, vcc
	v_cndmask_b32_e64 v66, v66, 0, s[0:1]
	v_cndmask_b32_e64 v67, v67, 0, s[0:1]
	v_cndmask_b32_e64 v68, v68, 0, s[0:1]
	v_cndmask_b32_e64 v69, v69, 0, s[0:1]
	v_cndmask_b32_e64 v72, v72, 0, s[0:1]
	v_cndmask_b32_e64 v73, v73, 0, s[0:1]
	v_cndmask_b32_e64 v74, v74, 0, s[0:1]
	v_cndmask_b32_e64 v75, v75, 0, s[0:1]
	s_waitcnt lgkmcnt(0)
	v_pk_fma_f32 v[78:79], v[204:205], v[108:109], v[78:79]
	v_pk_fma_f32 v[76:77], v[202:203], v[106:107], v[76:77]
	v_pk_fma_f32 v[78:79], v[104:105], v[110:111], v[78:79]
	v_pk_fma_f32 v[76:77], v[102:103], v[88:89], v[76:77]
	v_pk_fma_f32 v[78:79], v[100:101], v[68:69], v[78:79]
	v_pk_fma_f32 v[76:77], v[98:99], v[66:67], v[76:77]
	v_mov_b64_e32 v[66:67], v[252:253]
	v_mov_b64_e32 v[68:69], v[254:255]
	v_exp_f32_e32 v71, v76
	v_cndmask_b32_e64 v86, v214, 0, vcc
	v_cndmask_b32_e64 v87, v215, 0, vcc
	v_cndmask_b32_e64 v88, v216, 0, vcc
	v_add_f32_e32 v71, 1.0, v71
	v_rcp_f32_e32 v71, v71
	v_cndmask_b32_e64 v89, v217, 0, vcc
	v_mul_f32_e32 v71, v76, v71
	s_nop 0
	v_pk_fma_f32 v[66:67], v[206:207], v[94:95], v[66:67]
	s_nop 0
	v_pk_fma_f32 v[66:67], v[90:91], v[86:87], v[66:67]
	v_pk_fma_f32 v[68:69], v[208:209], v[96:97], v[68:69]
	v_pk_fma_f32 v[66:67], v[80:81], v[72:73], v[66:67]
	v_pk_fma_f32 v[68:69], v[92:93], v[88:89], v[68:69]
	v_mul_f32_e32 v66, v66, v71
	v_exp_f32_e32 v71, v77
	v_pk_fma_f32 v[68:69], v[82:83], v[74:75], v[68:69]
	v_add_f32_e32 v71, 1.0, v71
	v_rcp_f32_e32 v71, v71
	s_nop 0
	v_mul_f32_e32 v71, v77, v71
	v_mul_f32_e32 v67, v67, v71
	v_exp_f32_e32 v71, v78
	v_cvt_pk_bf16_f32 v74, v66, v67
	s_nop 0
	v_add_f32_e32 v71, 1.0, v71
	v_rcp_f32_e32 v71, v71
	s_nop 0
	v_mul_f32_e32 v71, v78, v71
	v_mul_f32_e32 v68, v68, v71
	v_exp_f32_e32 v71, v79
	s_nop 0
	v_add_f32_e32 v71, 1.0, v71
	v_rcp_f32_e32 v71, v71
	s_nop 0
	v_mul_f32_e32 v71, v79, v71
	v_mul_f32_e32 v69, v69, v71
	v_cvt_pk_bf16_f32 v75, v68, v69
	ds_read_b32 v68, v227
	s_waitcnt lgkmcnt(0)
	v_and_b32_e32 v66, 15, v68
	v_lshl_add_u32 v249, v66, 10, v248
	v_lshlrev_b32_e32 v146, 2, v66
	v_lshl_add_u64 v[66:67], s[68:69], 0, v[146:147]
	v_lshl_add_u64 v[72:73], v[66:67], 0, v[114:115]
	v_and_b32_e32 v66, 16, v68
	v_cmp_eq_u32_e32 vcc, 0, v66
	v_and_b32_e32 v66, 32, v68
	v_cmp_eq_u32_e64 s[0:1], 0, v66
	ds_read_b128 v[66:69], v249
	ds_read_b128 v[252:255], v249 offset:512
	v_cndmask_b32_e64 v76, v202, 0, vcc
	v_cndmask_b32_e64 v77, v203, 0, vcc
	v_cndmask_b32_e64 v86, v204, 0, vcc
	v_cndmask_b32_e64 v87, v205, 0, vcc
	v_cndmask_b32_e64 v78, v210, 0, s[0:1]
	v_cndmask_b32_e64 v79, v211, 0, s[0:1]
	v_cndmask_b32_e64 v88, v212, 0, s[0:1]
	v_cndmask_b32_e64 v89, v213, 0, s[0:1]
	v_cndmask_b32_e64 v110, v216, 0, s[0:1]
	v_cndmask_b32_e64 v111, v217, 0, s[0:1]
	s_waitcnt lgkmcnt(0)
	v_pk_fma_f32 v[68:69], v[56:57], v[108:109], v[68:69]
	v_pk_fma_f32 v[66:67], v[54:55], v[106:107], v[66:67]
	v_pk_fma_f32 v[68:69], v[104:105], v[86:87], v[68:69]
	v_pk_fma_f32 v[66:67], v[102:103], v[76:77], v[66:67]
	v_pk_fma_f32 v[76:77], v[100:101], v[88:89], v[68:69]
	v_pk_fma_f32 v[78:79], v[98:99], v[78:79], v[66:67]
	v_mov_b64_e32 v[66:67], v[252:253]
	v_mov_b64_e32 v[68:69], v[254:255]
	v_exp_f32_e32 v71, v78
	v_cndmask_b32_e64 v72, v206, 0, vcc
	v_cndmask_b32_e64 v73, v207, 0, vcc
	v_cndmask_b32_e64 v86, v214, 0, s[0:1]
	v_add_f32_e32 v71, 1.0, v71
	v_rcp_f32_e32 v71, v71
	v_cndmask_b32_e64 v87, v215, 0, s[0:1]
	v_cndmask_b32_e64 v88, v208, 0, vcc
	v_cndmask_b32_e64 v89, v209, 0, vcc
	v_mul_f32_e32 v71, v78, v71
	s_nop 0
	v_pk_fma_f32 v[66:67], v[50:51], v[94:95], v[66:67]
	s_nop 0
	v_pk_fma_f32 v[66:67], v[90:91], v[72:73], v[66:67]
	v_pk_fma_f32 v[68:69], v[52:53], v[96:97], v[68:69]
	v_pk_fma_f32 v[66:67], v[80:81], v[86:87], v[66:67]
	v_pk_fma_f32 v[68:69], v[92:93], v[88:89], v[68:69]
	v_mul_f32_e32 v66, v66, v71
	v_exp_f32_e32 v71, v79
	v_pk_fma_f32 v[68:69], v[82:83], v[110:111], v[68:69]
	v_add_f32_e32 v71, 1.0, v71
	v_rcp_f32_e32 v71, v71
	s_nop 0
	v_mul_f32_e32 v71, v79, v71
	v_mul_f32_e32 v67, v67, v71
	v_exp_f32_e32 v71, v76
	s_nop 0
	v_add_f32_e32 v71, 1.0, v71
	v_rcp_f32_e32 v71, v71
	s_nop 0
	v_mul_f32_e32 v71, v76, v71
	v_mul_f32_e32 v71, v68, v71
	v_exp_f32_e32 v68, v77
	s_nop 0
	v_add_f32_e32 v68, 1.0, v68
	v_rcp_f32_e32 v68, v68
	s_nop 0
	v_mul_f32_e32 v68, v77, v68
	v_mul_f32_e32 v69, v69, v68
	v_cvt_pk_bf16_f32 v69, v71, v69
	ds_read_b32 v71, v229
	v_cvt_pk_bf16_f32 v68, v66, v67
	s_waitcnt lgkmcnt(0)
	v_and_b32_e32 v66, 15, v71
	v_lshl_add_u32 v249, v66, 10, v248
	v_lshlrev_b32_e32 v146, 2, v66
	v_lshl_add_u64 v[66:67], s[68:69], 0, v[146:147]
	v_lshl_add_u64 v[86:87], v[66:67], 0, v[114:115]
	ds_read_b128 v[76:79], v249
	ds_read_b128 v[252:255], v249 offset:512
	v_and_b32_e32 v66, 16, v71
	v_cmp_eq_u32_e32 vcc, 0, v66
	v_and_b32_e32 v66, 32, v71
	v_cmp_eq_u32_e64 s[62:63], 0, v66
	v_cndmask_b32_e64 v66, v54, 0, vcc
	v_cndmask_b32_e64 v67, v55, 0, vcc
	v_cndmask_b32_e64 v72, v202, 0, s[62:63]
	v_cndmask_b32_e64 v73, v203, 0, s[62:63]
	v_cndmask_b32_e64 v88, v56, 0, vcc
	v_cndmask_b32_e64 v89, v57, 0, vcc
	v_cndmask_b32_e64 v110, v204, 0, s[62:63]
	v_cndmask_b32_e64 v111, v205, 0, s[62:63]
	v_cndmask_b32_e64 v112, v208, 0, s[62:63]
	v_cndmask_b32_e64 v113, v209, 0, s[62:63]
	s_waitcnt lgkmcnt(0)
	v_pk_fma_f32 v[76:77], v[62:63], v[106:107], v[76:77]
	v_pk_fma_f32 v[78:79], v[64:65], v[108:109], v[78:79]
	v_pk_fma_f32 v[76:77], v[102:103], v[66:67], v[76:77]
	v_pk_fma_f32 v[66:67], v[104:105], v[88:89], v[78:79]
	v_pk_fma_f32 v[72:73], v[98:99], v[72:73], v[76:77]
	v_mov_b64_e32 v[76:77], v[252:253]
	v_mov_b64_e32 v[78:79], v[254:255]
	v_exp_f32_e32 v71, v72
	v_pk_fma_f32 v[66:67], v[100:101], v[110:111], v[66:67]
	v_cndmask_b32_e64 v110, v52, 0, vcc
	v_cndmask_b32_e64 v111, v53, 0, vcc
	v_add_f32_e32 v71, 1.0, v71
	v_rcp_f32_e32 v71, v71
	v_cndmask_b32_e64 v86, v50, 0, vcc
	v_cndmask_b32_e64 v87, v51, 0, vcc
	v_cndmask_b32_e64 v88, v206, 0, s[62:63]
	v_mul_f32_e32 v71, v72, v71
	v_exp_f32_e32 v72, v73
	v_cndmask_b32_e64 v89, v207, 0, s[62:63]
	s_andn2_b64 vcc, exec, s[12:13]
	v_add_f32_e32 v72, 1.0, v72
	v_rcp_f32_e32 v72, v72
	s_nop 0
	v_pk_fma_f32 v[78:79], v[60:61], v[96:97], v[78:79]
	v_mul_f32_e32 v72, v73, v72
	v_exp_f32_e32 v73, v66
	v_pk_fma_f32 v[78:79], v[92:93], v[110:111], v[78:79]
	v_pk_fma_f32 v[76:77], v[58:59], v[94:95], v[76:77]
	v_pk_fma_f32 v[78:79], v[82:83], v[112:113], v[78:79]
	v_add_f32_e32 v73, 1.0, v73
	v_rcp_f32_e32 v73, v73
	v_pk_fma_f32 v[76:77], v[90:91], v[86:87], v[76:77]
	v_mov_b32_e32 v110, 0
	v_pk_fma_f32 v[76:77], v[80:81], v[88:89], v[76:77]
	v_mul_f32_e32 v66, v66, v73
	v_exp_f32_e32 v73, v67
	v_mul_f32_e32 v66, v78, v66
	v_mul_f32_e32 v71, v76, v71
	v_mul_f32_e32 v72, v77, v72
	v_add_f32_e32 v73, 1.0, v73
	v_rcp_f32_e32 v73, v73
	v_mov_b32_e32 v76, 0
	v_mov_b32_e32 v77, 0
	v_mov_b32_e32 v78, 0
	v_mul_f32_e32 v67, v67, v73
	v_mul_f32_e32 v67, v79, v67
	v_cvt_pk_bf16_f32 v89, v66, v67
	v_cndmask_b32_e64 v66, 0, 1, s[12:13]
	v_cmp_ne_u32_e64 s[62:63], 1, v66
	v_mov_b32_e32 v79, 0
	v_mov_b32_e32 v111, 0
	v_mov_b32_e32 v112, 0
	v_mov_b32_e32 v113, 0
	v_cvt_pk_bf16_f32 v88, v71, v72
	s_cbranch_vccnz .LBB0_1200
	ds_read_b128 v[110:113], v219 offset:3072
	ds_read_b128 v[76:79], v219 offset:2048

.LBB0_1202:
	ds_read_b32 v86, v231
	s_waitcnt lgkmcnt(2)
	v_mov_b32_dpp v118, v46 row_shr:1 row_mask:0xf bank_mask:0xf
	v_mov_b32_dpp v119, v47 row_shr:1 row_mask:0xf bank_mask:0xf
	s_waitcnt lgkmcnt(1)
	v_mov_b32_dpp v70, v38 row_shr:1 row_mask:0xf bank_mask:0xf
	v_mov_b32_dpp v71, v39 row_shr:1 row_mask:0xf bank_mask:0xf
	s_waitcnt lgkmcnt(0)
	v_and_b32_e32 v66, 15, v86
	v_lshl_add_u32 v249, v66, 10, v248
	v_lshlrev_b32_e32 v146, 2, v66
	v_lshl_add_u64 v[66:67], s[68:69], 0, v[146:147]
	v_lshl_add_u64 v[66:67], v[66:67], 0, v[114:115]
	ds_read_b128 v[122:125], v249
	ds_read_b128 v[252:255], v249 offset:512
	v_and_b32_e32 v87, 16, v86
	v_cmp_eq_u32_e32 vcc, 0, v87
	v_and_b32_e32 v86, 32, v86
	v_cmp_eq_u32_e64 s[0:1], 0, v86
	v_cndmask_b32_e64 v86, v110, 0, vcc
	v_cndmask_b32_e64 v87, v111, 0, vcc
	v_cndmask_b32_e64 v126, v112, 0, vcc
	v_cndmask_b32_e64 v127, v113, 0, vcc
	v_cndmask_b32_e64 v76, v76, 0, s[0:1]
	v_cndmask_b32_e64 v77, v77, 0, s[0:1]
	v_cndmask_b32_e64 v78, v78, 0, s[0:1]
	v_cndmask_b32_e64 v79, v79, 0, s[0:1]
	v_cndmask_b32_e64 v70, v70, 0, s[0:1]
	v_cndmask_b32_e64 v71, v71, 0, s[0:1]
	v_mov_b32_dpp v120, v48 row_shr:1 row_mask:0xf bank_mask:0xf
	v_mov_b32_dpp v121, v49 row_shr:1 row_mask:0xf bank_mask:0xf
	v_mov_b32_dpp v72, v40 row_shr:1 row_mask:0xf bank_mask:0xf
	v_mov_b32_dpp v73, v41 row_shr:1 row_mask:0xf bank_mask:0xf
	v_cndmask_b32_e64 v72, v72, 0, s[0:1]
	v_cndmask_b32_e64 v73, v73, 0, s[0:1]
	v_mov_b32_e32 v116, 0
	v_mov_b32_e32 v128, 0
	v_mov_b32_e32 v129, 0
	v_mov_b32_e32 v130, 0
	v_mov_b32_e32 v131, 0
	s_waitcnt lgkmcnt(0)
	v_pk_fma_f32 v[124:125], v[196:197], v[108:109], v[124:125]
	v_pk_fma_f32 v[122:123], v[194:195], v[106:107], v[122:123]
	s_nop 0
	v_pk_fma_f32 v[86:87], v[102:103], v[86:87], v[122:123]
	v_pk_fma_f32 v[122:123], v[104:105], v[126:127], v[124:125]
	v_pk_fma_f32 v[86:87], v[98:99], v[76:77], v[86:87]
	v_pk_fma_f32 v[122:123], v[100:101], v[78:79], v[122:123]
	v_mov_b64_e32 v[76:77], v[252:253]
	v_mov_b64_e32 v[78:79], v[254:255]
	v_cndmask_b32_e64 v66, v118, 0, vcc
	v_cndmask_b32_e64 v67, v119, 0, vcc
	v_cndmask_b32_e64 v124, v120, 0, vcc
	v_cndmask_b32_e64 v125, v121, 0, vcc
	v_mov_b32_e32 v126, 0
	v_mov_b32_e32 v127, 0
	s_nop 0
	v_pk_fma_f32 v[76:77], v[198:199], v[94:95], v[76:77]
	s_nop 0
	v_pk_fma_f32 v[66:67], v[90:91], v[66:67], v[76:77]
	v_pk_fma_f32 v[78:79], v[200:201], v[96:97], v[78:79]
	v_pk_fma_f32 v[66:67], v[80:81], v[70:71], v[66:67]
	v_exp_f32_e32 v70, v86
	v_exp_f32_e32 v71, v123
	v_pk_fma_f32 v[78:79], v[92:93], v[124:125], v[78:79]
	v_add_f32_e32 v70, 1.0, v70
	v_rcp_f32_e32 v70, v70
	v_add_f32_e32 v71, 1.0, v71
	v_rcp_f32_e32 v71, v71
	v_pk_fma_f32 v[72:73], v[82:83], v[72:73], v[78:79]
	v_mul_f32_e32 v70, v86, v70
	v_mul_f32_e32 v66, v66, v70
	v_exp_f32_e32 v70, v87
	v_mul_f32_e32 v71, v123, v71
	v_mul_f32_e32 v71, v73, v71
	v_mov_b32_e32 v124, 0
	v_add_f32_e32 v70, 1.0, v70
	v_rcp_f32_e32 v70, v70
	v_mov_b32_e32 v125, 0
	v_mul_f32_e32 v70, v87, v70
	v_mul_f32_e32 v67, v67, v70
	v_exp_f32_e32 v70, v122
	v_cvt_pk_bf16_f32 v78, v66, v67
	s_nop 0
	v_add_f32_e32 v70, 1.0, v70
	v_rcp_f32_e32 v70, v70
	s_nop 0
	v_mul_f32_e32 v70, v122, v70
	v_mul_f32_e32 v70, v72, v70
	v_cvt_pk_bf16_f32 v79, v70, v71
	ds_read_b32 v70, v233
	s_waitcnt lgkmcnt(0)
	v_and_b32_e32 v66, 15, v70
	v_lshl_add_u32 v249, v66, 10, v248
	v_lshlrev_b32_e32 v146, 2, v66
	v_lshl_add_u64 v[66:67], s[68:69], 0, v[146:147]
	v_lshl_add_u64 v[66:67], v[66:67], 0, v[114:115]
	v_and_b32_e32 v71, 16, v70
	v_and_b32_e32 v70, 32, v70
	v_cmp_eq_u32_e32 vcc, 0, v71
	v_cmp_eq_u32_e64 s[0:1], 0, v70
	ds_read_b128 v[70:73], v249
	ds_read_b128 v[252:255], v249 offset:512
	v_cndmask_b32_e64 v76, v194, 0, vcc
	v_cndmask_b32_e64 v86, v110, 0, s[0:1]
	v_cndmask_b32_e64 v77, v195, 0, vcc
	v_cndmask_b32_e64 v87, v111, 0, s[0:1]
	v_cndmask_b32_e64 v110, v196, 0, vcc
	v_cndmask_b32_e64 v111, v197, 0, vcc
	v_cndmask_b32_e64 v112, v112, 0, s[0:1]
	v_cndmask_b32_e64 v113, v113, 0, s[0:1]
	s_waitcnt lgkmcnt(0)
	v_pk_fma_f32 v[72:73], v[188:189], v[108:109], v[72:73]
	v_pk_fma_f32 v[70:71], v[186:187], v[106:107], v[70:71]
	v_pk_fma_f32 v[72:73], v[104:105], v[110:111], v[72:73]
	v_pk_fma_f32 v[70:71], v[102:103], v[76:77], v[70:71]
	v_pk_fma_f32 v[76:77], v[100:101], v[112:113], v[72:73]
	v_pk_fma_f32 v[86:87], v[98:99], v[86:87], v[70:71]
	v_mov_b64_e32 v[70:71], v[252:253]
	v_mov_b64_e32 v[72:73], v[254:255]
	v_cndmask_b32_e64 v66, v198, 0, vcc
	v_cndmask_b32_e64 v67, v199, 0, vcc
	v_cndmask_b32_e64 v112, v200, 0, vcc
	v_cndmask_b32_e64 v113, v201, 0, vcc
	v_cndmask_b32_e64 v110, v118, 0, s[0:1]
	v_cndmask_b32_e64 v111, v119, 0, s[0:1]
	v_cndmask_b32_e64 v118, v120, 0, s[0:1]
	v_cndmask_b32_e64 v119, v121, 0, s[0:1]
	s_nop 0
	v_pk_fma_f32 v[72:73], v[192:193], v[96:97], v[72:73]
	v_pk_fma_f32 v[70:71], v[190:191], v[94:95], v[70:71]
	s_nop 0
	v_pk_fma_f32 v[66:67], v[90:91], v[66:67], v[70:71]
	v_pk_fma_f32 v[70:71], v[92:93], v[112:113], v[72:73]
	v_exp_f32_e32 v72, v86
	v_pk_fma_f32 v[66:67], v[80:81], v[110:111], v[66:67]
	v_pk_fma_f32 v[70:71], v[82:83], v[118:119], v[70:71]
	v_add_f32_e32 v72, 1.0, v72
	v_rcp_f32_e32 v72, v72
	s_nop 0
	v_mul_f32_e32 v72, v86, v72
	v_mul_f32_e32 v66, v66, v72
	v_exp_f32_e32 v72, v87
	s_nop 0
	v_add_f32_e32 v72, 1.0, v72
	v_rcp_f32_e32 v72, v72
	s_nop 0
	v_mul_f32_e32 v72, v87, v72
	v_mul_f32_e32 v67, v67, v72
	v_exp_f32_e32 v72, v76
	s_nop 0
	v_add_f32_e32 v72, 1.0, v72
	v_rcp_f32_e32 v72, v72
	s_nop 0
	v_mul_f32_e32 v72, v76, v72
	v_mul_f32_e32 v70, v70, v72
	v_exp_f32_e32 v72, v77
	s_nop 0
	v_add_f32_e32 v72, 1.0, v72
	v_rcp_f32_e32 v72, v72
	s_nop 0
	v_mul_f32_e32 v72, v77, v72
	v_mul_f32_e32 v71, v71, v72
	v_cvt_pk_bf16_f32 v73, v70, v71
	ds_read_b32 v70, v235
	v_cvt_pk_bf16_f32 v72, v66, v67
	s_waitcnt lgkmcnt(0)
	v_and_b32_e32 v66, 15, v70
	v_lshl_add_u32 v249, v66, 10, v248
	v_lshlrev_b32_e32 v146, 2, v66
	v_lshl_add_u64 v[66:67], s[68:69], 0, v[146:147]
	v_lshl_add_u64 v[66:67], v[66:67], 0, v[114:115]
	ds_read_b128 v[110:113], v249
	ds_read_b128 v[252:255], v249 offset:512
	v_and_b32_e32 v71, 16, v70
	v_cmp_eq_u32_e32 vcc, 0, v71
	v_and_b32_e32 v70, 32, v70
	v_cmp_eq_u32_e64 s[0:1], 0, v70
	v_cndmask_b32_e64 v70, v186, 0, vcc
	v_cndmask_b32_e64 v71, v187, 0, vcc
	v_cndmask_b32_e64 v86, v188, 0, vcc
	v_cndmask_b32_e64 v87, v189, 0, vcc
	v_cndmask_b32_e64 v76, v194, 0, s[0:1]
	v_cndmask_b32_e64 v77, v195, 0, s[0:1]
	v_cndmask_b32_e64 v118, v196, 0, s[0:1]
	v_cndmask_b32_e64 v119, v197, 0, s[0:1]
	v_cndmask_b32_e64 v120, v200, 0, s[0:1]
	v_cndmask_b32_e64 v121, v201, 0, s[0:1]
	s_waitcnt lgkmcnt(0)
	v_pk_fma_f32 v[112:113], v[36:37], v[108:109], v[112:113]
	v_pk_fma_f32 v[110:111], v[34:35], v[106:107], v[110:111]
	v_pk_fma_f32 v[86:87], v[104:105], v[86:87], v[112:113]
	v_pk_fma_f32 v[70:71], v[102:103], v[70:71], v[110:111]
	v_mov_b64_e32 v[110:111], v[252:253]
	v_mov_b64_e32 v[112:113], v[254:255]
	v_cndmask_b32_e64 v66, v190, 0, vcc
	v_cndmask_b32_e64 v67, v191, 0, vcc
	v_pk_fma_f32 v[70:71], v[98:99], v[76:77], v[70:71]
	v_cndmask_b32_e64 v76, v198, 0, s[0:1]
	v_cndmask_b32_e64 v77, v199, 0, s[0:1]
	v_pk_fma_f32 v[86:87], v[100:101], v[118:119], v[86:87]
	v_cndmask_b32_e64 v118, v192, 0, vcc
	v_cndmask_b32_e64 v119, v193, 0, vcc
	s_nop 0
	v_pk_fma_f32 v[110:111], v[38:39], v[94:95], v[110:111]
	s_nop 0
	v_pk_fma_f32 v[66:67], v[90:91], v[66:67], v[110:111]
	v_pk_fma_f32 v[112:113], v[40:41], v[96:97], v[112:113]
	v_pk_fma_f32 v[66:67], v[80:81], v[76:77], v[66:67]
	v_exp_f32_e32 v76, v70
	v_pk_fma_f32 v[110:111], v[92:93], v[118:119], v[112:113]
	v_add_f32_e32 v76, 1.0, v76
	v_rcp_f32_e32 v76, v76
	v_pk_fma_f32 v[110:111], v[82:83], v[120:121], v[110:111]
	v_mul_f32_e32 v70, v70, v76
	v_mul_f32_e32 v66, v66, v70
	v_exp_f32_e32 v70, v71
	ds_read_b32 v76, v237
	v_add_f32_e32 v70, 1.0, v70
	v_rcp_f32_e32 v70, v70
	s_waitcnt lgkmcnt(0)
	v_and_b32_e32 v77, 16, v76
	v_cmp_eq_u32_e32 vcc, 0, v77
	v_mul_f32_e32 v70, v71, v70
	v_mul_f32_e32 v67, v67, v70
	v_exp_f32_e32 v70, v86
	v_exp_f32_e32 v71, v87
	v_cvt_pk_bf16_f32 v66, v66, v67
	v_add_f32_e32 v70, 1.0, v70
	v_rcp_f32_e32 v70, v70
	v_add_f32_e32 v71, 1.0, v71
	v_rcp_f32_e32 v71, v71
	v_cndmask_b32_e64 v77, v35, 0, vcc
	v_mul_f32_e32 v70, v86, v70
	v_mul_f32_e32 v70, v110, v70
	v_mul_f32_e32 v71, v87, v71
	v_mul_f32_e32 v71, v111, v71
	v_cvt_pk_bf16_f32 v67, v70, v71
	v_and_b32_e32 v70, 15, v76
	v_lshl_add_u32 v249, v70, 10, v248
	v_lshlrev_b32_e32 v146, 2, v70
	v_lshl_add_u64 v[70:71], s[68:69], 0, v[146:147]
	v_lshl_add_u64 v[70:71], v[70:71], 0, v[114:115]
	ds_read_b128 v[110:113], v249
	ds_read_b128 v[252:255], v249 offset:512
	v_and_b32_e32 v76, 32, v76
	v_cmp_eq_u32_e64 s[64:65], 0, v76
	v_cndmask_b32_e64 v76, v34, 0, vcc
	v_cndmask_b32_e64 v114, v36, 0, vcc
	v_cndmask_b32_e64 v115, v37, 0, vcc
	v_cndmask_b32_e64 v86, v186, 0, s[64:65]
	v_cndmask_b32_e64 v87, v187, 0, s[64:65]
	v_cndmask_b32_e64 v118, v188, 0, s[64:65]
	v_cndmask_b32_e64 v119, v189, 0, s[64:65]
	s_waitcnt lgkmcnt(0)
	v_pk_fma_f32 v[108:109], v[44:45], v[108:109], v[112:113]
	v_pk_fma_f32 v[106:107], v[42:43], v[106:107], v[110:111]
	s_nop 0
	v_pk_fma_f32 v[76:77], v[102:103], v[76:77], v[106:107]
	v_pk_fma_f32 v[102:103], v[104:105], v[114:115], v[108:109]
	v_pk_fma_f32 v[76:77], v[98:99], v[86:87], v[76:77]
	v_pk_fma_f32 v[102:103], v[100:101], v[118:119], v[102:103]
	v_mov_b64_e32 v[98:99], v[252:253]
	v_mov_b64_e32 v[100:101], v[254:255]
	v_cndmask_b32_e64 v70, v38, 0, vcc
	v_cndmask_b32_e64 v71, v39, 0, vcc
	v_cndmask_b32_e64 v86, v190, 0, s[64:65]
	v_cndmask_b32_e64 v87, v191, 0, s[64:65]
	v_cndmask_b32_e64 v104, v40, 0, vcc
	v_cndmask_b32_e64 v105, v41, 0, vcc
	v_cndmask_b32_e64 v106, v192, 0, s[64:65]
	v_cndmask_b32_e64 v107, v193, 0, s[64:65]
	s_and_b64 vcc, exec, s[60:61]
	s_nop 0
	v_pk_fma_f32 v[94:95], v[46:47], v[94:95], v[98:99]
	s_nop 0
	v_pk_fma_f32 v[70:71], v[90:91], v[70:71], v[94:95]
	v_pk_fma_f32 v[96:97], v[48:49], v[96:97], v[100:101]
	v_pk_fma_f32 v[70:71], v[80:81], v[86:87], v[70:71]
	v_exp_f32_e32 v80, v76
	v_pk_fma_f32 v[90:91], v[92:93], v[104:105], v[96:97]
	v_add_f32_e32 v80, 1.0, v80
	v_rcp_f32_e32 v80, v80
	v_pk_fma_f32 v[82:83], v[82:83], v[106:107], v[90:91]
	v_mul_f32_e32 v76, v76, v80
	v_mul_f32_e32 v70, v70, v76
	v_exp_f32_e32 v76, v77
	s_nop 0
	v_add_f32_e32 v76, 1.0, v76
	v_rcp_f32_e32 v76, v76
	s_nop 0
	v_mul_f32_e32 v76, v77, v76
	v_mul_f32_e32 v71, v71, v76
	v_exp_f32_e32 v76, v102
	v_exp_f32_e32 v77, v103
	v_add_f32_e32 v76, 1.0, v76
	v_rcp_f32_e32 v76, v76
	v_add_f32_e32 v77, 1.0, v77
	v_rcp_f32_e32 v77, v77
	v_mul_f32_e32 v76, v102, v76
	v_mul_f32_e32 v76, v82, v76
	v_cvt_pk_bf16_f32 v82, v70, v71
	v_or_b32_e32 v70, 4, v184
	v_mul_f32_e32 v77, v103, v77
	v_ashrrev_i32_e32 v71, 31, v70
	v_mul_f32_e32 v77, v83, v77
	v_lshlrev_b64 v[70:71], 2, v[70:71]
	v_cvt_pk_bf16_f32 v83, v76, v77
	v_lshl_add_u64 v[76:77], s[4:5], 0, v[70:71]
	global_load_dwordx4 v[104:107], v[76:77], off
	v_lshl_add_u64 v[76:77], s[96:97], 0, v[70:71]
	v_lshl_add_u64 v[70:71], s[78:79], 0, v[70:71]
	global_load_dwordx4 v[108:111], v[76:77], off
	global_load_dwordx4 v[112:115], v[70:71], off
	v_or_b32_e32 v70, 0x84, v184
	v_ashrrev_i32_e32 v71, 31, v70
	v_lshlrev_b64 v[70:71], 2, v[70:71]
	v_lshl_add_u64 v[76:77], s[4:5], 0, v[70:71]
	global_load_dwordx4 v[92:95], v[76:77], off
	v_lshl_add_u64 v[76:77], s[96:97], 0, v[70:71]
	v_lshl_add_u64 v[70:71], s[78:79], 0, v[70:71]
	global_load_dwordx4 v[96:99], v[76:77], off
	global_load_dwordx4 v[100:103], v[70:71], off
	s_cbranch_vccnz .LBB0_1204
	ds_read_b128 v[124:127], v221 offset:16
	ds_read_b128 v[128:131], v222 offset:16

.LBB0_1206:
	ds_read_b32 v243, v223
	s_waitcnt lgkmcnt(2)
	v_mov_b32_dpp v120, v26 row_shr:1 row_mask:0xf bank_mask:0xf
	v_mov_b32_dpp v121, v27 row_shr:1 row_mask:0xf bank_mask:0xf
	s_waitcnt lgkmcnt(1)
	v_mov_b32_dpp v116, v18 row_shr:1 row_mask:0xf bank_mask:0xf
	v_mov_b32_dpp v117, v19 row_shr:1 row_mask:0xf bank_mask:0xf
	s_waitcnt lgkmcnt(0)
	v_and_b32_e32 v70, 15, v243
	v_lshl_add_u32 v249, v70, 10, v248
	v_lshlrev_b32_e32 v146, 2, v70
	v_lshl_add_u64 v[70:71], s[68:69], 0, v[146:147]
	v_lshl_add_u64 v[70:71], v[184:185], 2, v[70:71]
	ds_read_b128 v[244:247], v249 offset:16
	ds_read_b128 v[252:255], v249 offset:528
	v_and_b32_e32 v76, 16, v243
	v_cmp_eq_u32_e32 vcc, 0, v76
	v_and_b32_e32 v76, 32, v243
	v_cmp_eq_u32_e64 s[0:1], 0, v76
	v_cndmask_b32_e64 v76, v124, 0, vcc
	v_cndmask_b32_e64 v77, v125, 0, vcc
	v_cndmask_b32_e64 v80, v128, 0, s[0:1]
	v_cndmask_b32_e64 v81, v129, 0, s[0:1]
	v_cndmask_b32_e64 v86, v126, 0, vcc
	v_cndmask_b32_e64 v90, v130, 0, s[0:1]
	v_cndmask_b32_e64 v87, v127, 0, vcc
	v_cndmask_b32_e64 v91, v131, 0, s[0:1]
	v_mov_b32_dpp v122, v28 row_shr:1 row_mask:0xf bank_mask:0xf
	v_mov_b32_dpp v118, v20 row_shr:1 row_mask:0xf bank_mask:0xf
	v_mov_b32_dpp v123, v29 row_shr:1 row_mask:0xf bank_mask:0xf
	v_mov_b32_dpp v119, v21 row_shr:1 row_mask:0xf bank_mask:0xf
	s_waitcnt vmcnt(0) lgkmcnt(0)
	v_pk_fma_f32 v[128:129], v[182:183], v[114:115], v[246:247]
	v_pk_fma_f32 v[130:131], v[178:179], v[112:113], v[244:245]
	v_pk_fma_f32 v[86:87], v[110:111], v[86:87], v[128:129]
	v_pk_fma_f32 v[76:77], v[108:109], v[76:77], v[130:131]
	v_mov_b64_e32 v[128:129], v[252:253]
	v_mov_b64_e32 v[130:131], v[254:255]
	v_cndmask_b32_e64 v70, v120, 0, vcc
	v_cndmask_b32_e64 v71, v121, 0, vcc
	v_pk_fma_f32 v[76:77], v[104:105], v[80:81], v[76:77]
	v_cndmask_b32_e64 v80, v116, 0, s[0:1]
	v_cndmask_b32_e64 v81, v117, 0, s[0:1]
	v_pk_fma_f32 v[86:87], v[106:107], v[90:91], v[86:87]
	v_cndmask_b32_e64 v90, v122, 0, vcc
	v_cndmask_b32_e64 v116, v118, 0, s[0:1]
	v_cndmask_b32_e64 v91, v123, 0, vcc
	v_cndmask_b32_e64 v117, v119, 0, s[0:1]
	s_nop 0
	v_pk_fma_f32 v[128:129], v[176:177], v[100:101], v[128:129]
	s_nop 0
	v_pk_fma_f32 v[70:71], v[96:97], v[70:71], v[128:129]
	v_pk_fma_f32 v[118:119], v[180:181], v[102:103], v[130:131]
	v_pk_fma_f32 v[70:71], v[92:93], v[80:81], v[70:71]
	v_exp_f32_e32 v80, v76
	v_pk_fma_f32 v[90:91], v[98:99], v[90:91], v[118:119]
	v_add_f32_e32 v80, 1.0, v80
	v_rcp_f32_e32 v80, v80
	v_pk_fma_f32 v[90:91], v[94:95], v[116:117], v[90:91]
	v_mul_f32_e32 v76, v76, v80
	v_mul_f32_e32 v70, v70, v76
	v_exp_f32_e32 v76, v77
	s_nop 0
	v_add_f32_e32 v76, 1.0, v76
	v_rcp_f32_e32 v76, v76
	s_nop 0
	v_mul_f32_e32 v76, v77, v76
	v_mul_f32_e32 v71, v71, v76
	v_exp_f32_e32 v76, v86
	v_exp_f32_e32 v77, v87
	v_add_f32_e32 v76, 1.0, v76
	v_rcp_f32_e32 v76, v76
	v_add_f32_e32 v77, 1.0, v77
	v_rcp_f32_e32 v77, v77
	v_mul_f32_e32 v76, v86, v76
	v_cvt_pk_bf16_f32 v86, v70, v71
	v_and_b32_e32 v70, 64, v243
	v_mul_f32_e32 v77, v87, v77
	v_cmp_ne_u32_e32 vcc, 0, v70
	v_mul_f32_e32 v76, v90, v76
	v_mul_f32_e32 v77, v91, v77
	v_cvt_pk_bf16_f32 v87, v76, v77
	s_and_saveexec_b64 s[0:1], vcc
	s_cbranch_execz .LBB0_1208
	v_add_u32_e32 v76, s17, v220
	v_mov_b64_e32 v[70:71], s[70:71]
	v_mad_i64_i32 v[70:71], s[38:39], v76, s34, v[70:71]
	s_lshl_b32 s38, s72, 7
	s_ashr_i32 s39, s38, 31
	v_lshl_add_u64 v[70:71], s[38:39], 1, v[70:71]
	v_lshlrev_b32_e32 v146, 1, v148
	v_lshl_add_u64 v[70:71], v[70:71], 0, v[146:147]
	global_store_dwordx4 v[70:71], v[84:87], off
.LBB0_1208:
	s_or_b64 exec, exec, s[0:1]
	ds_read_b32 v128, v225
	s_waitcnt lgkmcnt(0)
	v_and_b32_e32 v70, 15, v128
	v_lshl_add_u32 v249, v70, 10, v248
	v_lshlrev_b32_e32 v146, 2, v70
	v_lshl_add_u64 v[70:71], s[68:69], 0, v[146:147]
	v_lshl_add_u64 v[70:71], v[184:185], 2, v[70:71]
	ds_read_b128 v[84:87], v249 offset:16
	ds_read_b128 v[252:255], v249 offset:528
	v_and_b32_e32 v76, 16, v128
	v_cmp_eq_u32_e32 vcc, 0, v76
	v_and_b32_e32 v76, 32, v128
	v_cmp_eq_u32_e64 s[0:1], 0, v76
	v_cndmask_b32_e64 v90, v182, 0, vcc
	v_cndmask_b32_e64 v91, v183, 0, vcc
	v_cndmask_b32_e64 v76, v178, 0, vcc
	v_cndmask_b32_e64 v77, v179, 0, vcc
	v_cndmask_b32_e64 v116, v126, 0, s[0:1]
	v_cndmask_b32_e64 v117, v127, 0, s[0:1]
	v_cndmask_b32_e64 v80, v124, 0, s[0:1]
	v_cndmask_b32_e64 v81, v125, 0, s[0:1]
	v_cndmask_b32_e64 v118, v122, 0, s[0:1]
	v_cndmask_b32_e64 v119, v123, 0, s[0:1]
	s_waitcnt lgkmcnt(0)
	v_pk_fma_f32 v[86:87], v[174:175], v[114:115], v[86:87]
	v_pk_fma_f32 v[84:85], v[172:173], v[112:113], v[84:85]
	v_pk_fma_f32 v[86:87], v[110:111], v[90:91], v[86:87]
	v_pk_fma_f32 v[76:77], v[108:109], v[76:77], v[84:85]
	v_pk_fma_f32 v[90:91], v[106:107], v[116:117], v[86:87]
	v_mov_b64_e32 v[84:85], v[252:253]
	v_mov_b64_e32 v[86:87], v[254:255]
	v_cndmask_b32_e64 v70, v176, 0, vcc
	v_cndmask_b32_e64 v71, v177, 0, vcc
	v_pk_fma_f32 v[76:77], v[104:105], v[80:81], v[76:77]
	v_cndmask_b32_e64 v80, v120, 0, s[0:1]
	v_cndmask_b32_e64 v81, v121, 0, s[0:1]
	v_cndmask_b32_e64 v116, v180, 0, vcc
	v_cndmask_b32_e64 v117, v181, 0, vcc
	s_nop 0
	v_pk_fma_f32 v[84:85], v[168:169], v[100:101], v[84:85]
	s_nop 0
	v_pk_fma_f32 v[70:71], v[96:97], v[70:71], v[84:85]
	v_pk_fma_f32 v[86:87], v[170:171], v[102:103], v[86:87]
	v_pk_fma_f32 v[70:71], v[92:93], v[80:81], v[70:71]
	v_exp_f32_e32 v80, v76
	v_pk_fma_f32 v[86:87], v[98:99], v[116:117], v[86:87]
	v_add_f32_e32 v80, 1.0, v80
	v_rcp_f32_e32 v80, v80
	v_pk_fma_f32 v[84:85], v[94:95], v[118:119], v[86:87]
	v_mul_f32_e32 v76, v76, v80
	v_mul_f32_e32 v70, v70, v76
	v_exp_f32_e32 v76, v77
	s_nop 0
	v_add_f32_e32 v76, 1.0, v76
	v_rcp_f32_e32 v76, v76
	s_nop 0
	v_mul_f32_e32 v76, v77, v76
	v_mul_f32_e32 v71, v71, v76
	v_exp_f32_e32 v76, v90
	s_nop 0
	v_add_f32_e32 v76, 1.0, v76
	v_rcp_f32_e32 v76, v76
	s_nop 0
	v_mul_f32_e32 v76, v90, v76
	v_mul_f32_e32 v77, v84, v76
	v_exp_f32_e32 v76, v91
	s_nop 0
	v_add_f32_e32 v76, 1.0, v76
	v_rcp_f32_e32 v76, v76
	s_nop 0
	v_mul_f32_e32 v76, v91, v76
	v_mul_f32_e32 v80, v85, v76
	v_cvt_pk_bf16_f32 v76, v70, v71
	v_and_b32_e32 v70, 64, v128
	v_cmp_ne_u32_e32 vcc, 0, v70
	v_cvt_pk_bf16_f32 v77, v77, v80
	s_and_saveexec_b64 s[0:1], vcc
	s_cbranch_execz .LBB0_1210
	v_add_u32_e32 v80, s17, v224
	v_mov_b64_e32 v[70:71], s[70:71]
	v_mad_i64_i32 v[70:71], s[38:39], v80, s34, v[70:71]
	s_lshl_b32 s38, s72, 7
	s_ashr_i32 s39, s38, 31
	v_lshl_add_u64 v[70:71], s[38:39], 1, v[70:71]
	v_lshlrev_b32_e32 v146, 1, v148
	v_lshl_add_u64 v[70:71], v[70:71], 0, v[146:147]
	global_store_dwordx4 v[70:71], v[74:77], off
.LBB0_1210:
	s_or_b64 exec, exec, s[0:1]
	ds_read_b32 v118, v227
	s_waitcnt lgkmcnt(0)
	v_and_b32_e32 v70, 15, v118
	v_lshl_add_u32 v249, v70, 10, v248
	v_lshlrev_b32_e32 v146, 2, v70
	v_lshl_add_u64 v[70:71], s[68:69], 0, v[146:147]
	v_and_b32_e32 v74, 16, v118
	v_lshl_add_u64 v[70:71], v[184:185], 2, v[70:71]
	v_cmp_eq_u32_e32 vcc, 0, v74
	v_and_b32_e32 v74, 32, v118
	v_cmp_eq_u32_e64 s[0:1], 0, v74
	ds_read_b128 v[74:77], v249 offset:16
	ds_read_b128 v[252:255], v249 offset:528
	v_cndmask_b32_e64 v80, v172, 0, vcc
	v_cndmask_b32_e64 v81, v173, 0, vcc
	v_cndmask_b32_e64 v86, v174, 0, vcc
	v_cndmask_b32_e64 v87, v175, 0, vcc
	v_cndmask_b32_e64 v84, v178, 0, s[0:1]
	v_cndmask_b32_e64 v85, v179, 0, s[0:1]
	v_cndmask_b32_e64 v90, v182, 0, s[0:1]
	v_cndmask_b32_e64 v91, v183, 0, s[0:1]
	v_cndmask_b32_e64 v116, v180, 0, s[0:1]
	v_cndmask_b32_e64 v117, v181, 0, s[0:1]
	s_waitcnt lgkmcnt(0)
	v_pk_fma_f32 v[76:77], v[24:25], v[114:115], v[76:77]
	v_pk_fma_f32 v[74:75], v[22:23], v[112:113], v[74:75]
	v_pk_fma_f32 v[76:77], v[110:111], v[86:87], v[76:77]
	v_pk_fma_f32 v[74:75], v[108:109], v[80:81], v[74:75]
	v_pk_fma_f32 v[80:81], v[106:107], v[90:91], v[76:77]
	v_pk_fma_f32 v[84:85], v[104:105], v[84:85], v[74:75]
	v_mov_b64_e32 v[74:75], v[252:253]
	v_mov_b64_e32 v[76:77], v[254:255]
	v_cndmask_b32_e64 v90, v170, 0, vcc
	v_cndmask_b32_e64 v91, v171, 0, vcc
	v_cndmask_b32_e64 v70, v168, 0, vcc
	v_cndmask_b32_e64 v71, v169, 0, vcc
	v_cndmask_b32_e64 v86, v176, 0, s[0:1]
	v_cndmask_b32_e64 v87, v177, 0, s[0:1]
	s_nop 0
	v_pk_fma_f32 v[76:77], v[20:21], v[102:103], v[76:77]
	v_pk_fma_f32 v[74:75], v[18:19], v[100:101], v[74:75]
	v_pk_fma_f32 v[76:77], v[98:99], v[90:91], v[76:77]
	v_pk_fma_f32 v[70:71], v[96:97], v[70:71], v[74:75]
	v_pk_fma_f32 v[74:75], v[94:95], v[116:117], v[76:77]
	v_exp_f32_e32 v76, v84
	v_pk_fma_f32 v[70:71], v[92:93], v[86:87], v[70:71]
	v_add_f32_e32 v76, 1.0, v76
	v_rcp_f32_e32 v76, v76
	s_nop 0
	v_mul_f32_e32 v76, v84, v76
	v_mul_f32_e32 v70, v70, v76
	v_exp_f32_e32 v76, v85
	s_nop 0
	v_add_f32_e32 v76, 1.0, v76
	v_rcp_f32_e32 v76, v76
	s_nop 0
	v_mul_f32_e32 v76, v85, v76
	v_mul_f32_e32 v71, v71, v76
	v_exp_f32_e32 v76, v80
	v_cvt_pk_bf16_f32 v70, v70, v71
	s_nop 0
	v_add_f32_e32 v76, 1.0, v76
	v_rcp_f32_e32 v76, v76
	s_nop 0
	v_mul_f32_e32 v76, v80, v76
	v_mul_f32_e32 v74, v74, v76
	v_exp_f32_e32 v76, v81
	s_nop 0
	v_add_f32_e32 v76, 1.0, v76
	v_rcp_f32_e32 v76, v76
	s_nop 0
	v_mul_f32_e32 v76, v81, v76
	v_mul_f32_e32 v75, v75, v76
	v_cvt_pk_bf16_f32 v71, v74, v75
	v_and_b32_e32 v74, 64, v118
	v_cmp_ne_u32_e32 vcc, 0, v74
	s_and_saveexec_b64 s[0:1], vcc
	s_cbranch_execz .LBB0_1212
	v_add_u32_e32 v76, s17, v226
	v_mov_b64_e32 v[74:75], s[70:71]
	v_mad_i64_i32 v[74:75], s[38:39], v76, s34, v[74:75]
	s_lshl_b32 s38, s72, 7
	s_ashr_i32 s39, s38, 31
	v_lshl_add_u64 v[74:75], s[38:39], 1, v[74:75]
	v_lshlrev_b32_e32 v146, 1, v148
	v_lshl_add_u64 v[74:75], v[74:75], 0, v[146:147]
	global_store_dwordx4 v[74:75], v[68:71], off
.LBB0_1212:
	s_or_b64 exec, exec, s[0:1]
	ds_read_b32 v116, v229
	s_waitcnt lgkmcnt(0)
	v_and_b32_e32 v68, 15, v116
	v_lshl_add_u32 v249, v68, 10, v248
	v_lshlrev_b32_e32 v146, 2, v68
	v_lshl_add_u64 v[68:69], s[68:69], 0, v[146:147]
	v_lshl_add_u64 v[74:75], v[184:185], 2, v[68:69]
	v_and_b32_e32 v68, 16, v116
	v_cmp_eq_u32_e32 vcc, 0, v68
	v_and_b32_e32 v68, 32, v116
	v_cmp_eq_u32_e64 s[0:1], 0, v68
	ds_read_b128 v[68:71], v249 offset:16
	ds_read_b128 v[252:255], v249 offset:528
	v_cndmask_b32_e64 v76, v22, 0, vcc
	v_cndmask_b32_e64 v77, v23, 0, vcc
	v_cndmask_b32_e64 v84, v24, 0, vcc
	v_cndmask_b32_e64 v85, v25, 0, vcc
	v_cndmask_b32_e64 v80, v172, 0, s[0:1]
	v_cndmask_b32_e64 v81, v173, 0, s[0:1]
	v_cndmask_b32_e64 v86, v174, 0, s[0:1]
	v_cndmask_b32_e64 v87, v175, 0, s[0:1]
	v_cndmask_b32_e64 v90, v170, 0, s[0:1]
	v_cndmask_b32_e64 v91, v171, 0, s[0:1]
	s_waitcnt lgkmcnt(0)
	v_pk_fma_f32 v[70:71], v[32:33], v[114:115], v[70:71]
	v_pk_fma_f32 v[68:69], v[30:31], v[112:113], v[68:69]
	v_pk_fma_f32 v[70:71], v[110:111], v[84:85], v[70:71]
	v_pk_fma_f32 v[68:69], v[108:109], v[76:77], v[68:69]
	v_pk_fma_f32 v[76:77], v[106:107], v[86:87], v[70:71]
	v_pk_fma_f32 v[80:81], v[104:105], v[80:81], v[68:69]
	v_mov_b64_e32 v[68:69], v[252:253]
	v_mov_b64_e32 v[70:71], v[254:255]
	v_cndmask_b32_e64 v74, v18, 0, vcc
	v_cndmask_b32_e64 v75, v19, 0, vcc
	v_cndmask_b32_e64 v84, v168, 0, s[0:1]
	v_cndmask_b32_e64 v85, v169, 0, s[0:1]
	v_cndmask_b32_e64 v86, v20, 0, vcc
	v_cndmask_b32_e64 v87, v21, 0, vcc
	s_nop 0
	v_pk_fma_f32 v[68:69], v[26:27], v[100:101], v[68:69]
	s_nop 0
	v_pk_fma_f32 v[68:69], v[96:97], v[74:75], v[68:69]
	v_exp_f32_e32 v74, v80
	v_pk_fma_f32 v[68:69], v[92:93], v[84:85], v[68:69]
	v_pk_fma_f32 v[70:71], v[28:29], v[102:103], v[70:71]
	v_add_f32_e32 v74, 1.0, v74
	v_rcp_f32_e32 v74, v74
	v_pk_fma_f32 v[70:71], v[98:99], v[86:87], v[70:71]
	v_mul_f32_e32 v74, v80, v74
	v_mul_f32_e32 v68, v68, v74
	v_exp_f32_e32 v74, v81
	v_pk_fma_f32 v[70:71], v[94:95], v[90:91], v[70:71]
	v_add_f32_e32 v74, 1.0, v74
	v_rcp_f32_e32 v74, v74
	s_nop 0
	v_mul_f32_e32 v74, v81, v74
	v_mul_f32_e32 v69, v69, v74
	v_exp_f32_e32 v74, v76
	v_cvt_pk_bf16_f32 v90, v68, v69
	v_and_b32_e32 v68, 64, v116
	v_cmp_ne_u32_e32 vcc, 0, v68
	v_add_f32_e32 v74, 1.0, v74
	v_rcp_f32_e32 v74, v74
	s_nop 0
	v_mul_f32_e32 v74, v76, v74
	v_mul_f32_e32 v70, v70, v74
	v_exp_f32_e32 v74, v77
	s_nop 0
	v_add_f32_e32 v74, 1.0, v74
	v_rcp_f32_e32 v74, v74
	s_nop 0
	v_mul_f32_e32 v74, v77, v74
	v_mul_f32_e32 v71, v71, v74
	v_cvt_pk_bf16_f32 v91, v70, v71
	s_and_saveexec_b64 s[0:1], vcc
	s_cbranch_execz .LBB0_1214
	v_add_u32_e32 v70, s17, v228
	v_mov_b64_e32 v[68:69], s[70:71]
	v_mad_i64_i32 v[68:69], s[38:39], v70, s34, v[68:69]
	s_lshl_b32 s38, s72, 7
	s_ashr_i32 s39, s38, 31
	v_lshl_add_u64 v[68:69], s[38:39], 1, v[68:69]
	v_lshlrev_b32_e32 v146, 1, v148
	v_lshl_add_u64 v[68:69], v[68:69], 0, v[146:147]
	global_store_dwordx4 v[68:69], v[88:91], off

.LBB0_1218:
	ds_read_b32 v124, v231
	s_waitcnt lgkmcnt(2)
	v_mov_b32_dpp v68, v14 row_shr:1 row_mask:0xf bank_mask:0xf
	v_mov_b32_dpp v69, v15 row_shr:1 row_mask:0xf bank_mask:0xf
	s_waitcnt lgkmcnt(1)
	v_mov_b32_dpp v84, v2 row_shr:1 row_mask:0xf bank_mask:0xf
	v_mov_b32_dpp v85, v3 row_shr:1 row_mask:0xf bank_mask:0xf
	s_waitcnt lgkmcnt(0)
	v_and_b32_e32 v80, 15, v124
	v_lshl_add_u32 v249, v80, 10, v248
	v_lshlrev_b32_e32 v146, 2, v80
	v_lshl_add_u64 v[80:81], s[68:69], 0, v[146:147]
	v_and_b32_e32 v116, 16, v124
	v_lshl_add_u64 v[80:81], v[184:185], 2, v[80:81]
	v_cmp_eq_u32_e32 vcc, 0, v116
	v_and_b32_e32 v116, 32, v124
	v_cmp_eq_u32_e64 s[0:1], 0, v116
	ds_read_b128 v[116:119], v249 offset:16
	ds_read_b128 v[252:255], v249 offset:528
	v_cndmask_b32_e64 v120, v74, 0, vcc
	v_cndmask_b32_e64 v121, v75, 0, vcc
	v_cndmask_b32_e64 v122, v76, 0, vcc
	v_cndmask_b32_e64 v123, v77, 0, vcc
	v_cndmask_b32_e64 v88, v88, 0, s[0:1]
	v_cndmask_b32_e64 v89, v89, 0, s[0:1]
	v_cndmask_b32_e64 v90, v90, 0, s[0:1]
	v_cndmask_b32_e64 v91, v91, 0, s[0:1]
	v_cndmask_b32_e64 v84, v84, 0, s[0:1]
	v_cndmask_b32_e64 v85, v85, 0, s[0:1]
	v_mov_b32_dpp v70, v16 row_shr:1 row_mask:0xf bank_mask:0xf
	v_mov_b32_dpp v71, v17 row_shr:1 row_mask:0xf bank_mask:0xf
	v_mov_b32_dpp v86, v4 row_shr:1 row_mask:0xf bank_mask:0xf
	v_mov_b32_dpp v87, v5 row_shr:1 row_mask:0xf bank_mask:0xf
	v_cndmask_b32_e64 v86, v86, 0, s[0:1]
	v_cndmask_b32_e64 v87, v87, 0, s[0:1]
	s_waitcnt lgkmcnt(0)
	v_pk_fma_f32 v[118:119], v[166:167], v[114:115], v[118:119]
	v_pk_fma_f32 v[116:117], v[162:163], v[112:113], v[116:117]
	v_pk_fma_f32 v[118:119], v[110:111], v[122:123], v[118:119]
	v_pk_fma_f32 v[116:117], v[108:109], v[120:121], v[116:117]
	v_pk_fma_f32 v[118:119], v[106:107], v[90:91], v[118:119]
	v_pk_fma_f32 v[116:117], v[104:105], v[88:89], v[116:117]
	v_mov_b64_e32 v[88:89], v[252:253]
	v_mov_b64_e32 v[90:91], v[254:255]
	v_cndmask_b32_e64 v80, v68, 0, vcc
	v_cndmask_b32_e64 v81, v69, 0, vcc
	v_cndmask_b32_e64 v120, v70, 0, vcc
	v_cndmask_b32_e64 v121, v71, 0, vcc
	s_nop 0
	v_pk_fma_f32 v[88:89], v[160:161], v[100:101], v[88:89]
	s_nop 0
	v_pk_fma_f32 v[80:81], v[96:97], v[80:81], v[88:89]
	v_pk_fma_f32 v[90:91], v[164:165], v[102:103], v[90:91]
	v_pk_fma_f32 v[80:81], v[92:93], v[84:85], v[80:81]
	v_exp_f32_e32 v84, v116
	v_exp_f32_e32 v85, v119
	v_pk_fma_f32 v[88:89], v[98:99], v[120:121], v[90:91]
	v_add_f32_e32 v84, 1.0, v84
	v_rcp_f32_e32 v84, v84
	v_add_f32_e32 v85, 1.0, v85
	v_rcp_f32_e32 v85, v85
	v_pk_fma_f32 v[86:87], v[94:95], v[86:87], v[88:89]
	v_mul_f32_e32 v84, v116, v84
	v_mul_f32_e32 v80, v80, v84
	v_exp_f32_e32 v84, v117
	v_mul_f32_e32 v85, v119, v85
	v_mul_f32_e32 v85, v87, v85
	v_add_f32_e32 v84, 1.0, v84
	v_rcp_f32_e32 v84, v84
	s_nop 0
	v_mul_f32_e32 v84, v117, v84
	v_mul_f32_e32 v81, v81, v84
	v_exp_f32_e32 v84, v118
	v_cvt_pk_bf16_f32 v80, v80, v81
	s_nop 0
	v_add_f32_e32 v84, 1.0, v84
	v_rcp_f32_e32 v84, v84
	s_nop 0
	v_mul_f32_e32 v84, v118, v84
	v_mul_f32_e32 v84, v86, v84
	v_cvt_pk_bf16_f32 v81, v84, v85
	v_and_b32_e32 v84, 64, v124
	v_cmp_ne_u32_e32 vcc, 0, v84
	s_and_saveexec_b64 s[0:1], vcc
	s_cbranch_execz .LBB0_1220
	v_add_u32_e32 v86, s17, v230
	v_mov_b64_e32 v[84:85], s[70:71]
	v_mad_i64_i32 v[84:85], s[38:39], v86, s34, v[84:85]
	s_lshl_b32 s38, s72, 7
	s_ashr_i32 s39, s38, 31
	v_lshl_add_u64 v[84:85], s[38:39], 1, v[84:85]
	v_lshlrev_b32_e32 v146, 1, v148
	v_lshl_add_u64 v[84:85], v[84:85], 0, v[146:147]
	global_store_dwordx4 v[84:85], v[78:81], off
.LBB0_1220:
	s_or_b64 exec, exec, s[0:1]
	ds_read_b32 v90, v233
	s_waitcnt lgkmcnt(0)
	v_and_b32_e32 v78, 15, v90
	v_lshl_add_u32 v249, v78, 10, v248
	v_lshlrev_b32_e32 v146, 2, v78
	v_lshl_add_u64 v[78:79], s[68:69], 0, v[146:147]
	v_lshl_add_u64 v[84:85], v[184:185], 2, v[78:79]
	v_and_b32_e32 v78, 16, v90
	v_cmp_eq_u32_e32 vcc, 0, v78
	v_and_b32_e32 v78, 32, v90
	v_cmp_eq_u32_e64 s[0:1], 0, v78
	ds_read_b128 v[78:81], v249 offset:16
	ds_read_b128 v[252:255], v249 offset:528
	v_cndmask_b32_e64 v86, v162, 0, vcc
	v_cndmask_b32_e64 v87, v163, 0, vcc
	v_cndmask_b32_e64 v88, v166, 0, vcc
	v_cndmask_b32_e64 v89, v167, 0, vcc
	v_cndmask_b32_e64 v74, v74, 0, s[0:1]
	v_cndmask_b32_e64 v75, v75, 0, s[0:1]
	v_cndmask_b32_e64 v76, v76, 0, s[0:1]
	v_cndmask_b32_e64 v77, v77, 0, s[0:1]
	v_cndmask_b32_e64 v68, v68, 0, s[0:1]
	v_cndmask_b32_e64 v69, v69, 0, s[0:1]
	v_cndmask_b32_e64 v70, v70, 0, s[0:1]
	v_cndmask_b32_e64 v71, v71, 0, s[0:1]
	s_waitcnt lgkmcnt(0)
	v_pk_fma_f32 v[80:81], v[158:159], v[114:115], v[80:81]
	v_pk_fma_f32 v[78:79], v[136:137], v[112:113], v[78:79]
	v_pk_fma_f32 v[80:81], v[110:111], v[88:89], v[80:81]
	v_pk_fma_f32 v[78:79], v[108:109], v[86:87], v[78:79]
	v_pk_fma_f32 v[80:81], v[106:107], v[76:77], v[80:81]
	v_pk_fma_f32 v[78:79], v[104:105], v[74:75], v[78:79]
	v_mov_b64_e32 v[74:75], v[252:253]
	v_mov_b64_e32 v[76:77], v[254:255]
	v_cndmask_b32_e64 v84, v160, 0, vcc
	v_cndmask_b32_e64 v85, v161, 0, vcc
	v_cndmask_b32_e64 v86, v164, 0, vcc
	v_cndmask_b32_e64 v87, v165, 0, vcc
	s_nop 0
	v_pk_fma_f32 v[74:75], v[132:133], v[100:101], v[74:75]
	s_nop 0
	v_pk_fma_f32 v[74:75], v[96:97], v[84:85], v[74:75]
	v_pk_fma_f32 v[76:77], v[134:135], v[102:103], v[76:77]
	v_pk_fma_f32 v[68:69], v[92:93], v[68:69], v[74:75]
	v_exp_f32_e32 v74, v78
	v_pk_fma_f32 v[76:77], v[98:99], v[86:87], v[76:77]
	v_add_f32_e32 v74, 1.0, v74
	v_rcp_f32_e32 v74, v74
	v_pk_fma_f32 v[70:71], v[94:95], v[70:71], v[76:77]
	v_mul_f32_e32 v74, v78, v74
	v_mul_f32_e32 v68, v68, v74
	v_exp_f32_e32 v74, v79
	s_nop 0
	v_add_f32_e32 v74, 1.0, v74
	v_rcp_f32_e32 v74, v74
	s_nop 0
	v_mul_f32_e32 v74, v79, v74
	v_mul_f32_e32 v69, v69, v74
	v_exp_f32_e32 v74, v80
	s_nop 0
	v_add_f32_e32 v74, 1.0, v74
	v_rcp_f32_e32 v74, v74
	s_nop 0
	v_mul_f32_e32 v74, v80, v74
	v_mul_f32_e32 v70, v70, v74
	v_exp_f32_e32 v74, v81
	s_nop 0
	v_add_f32_e32 v74, 1.0, v74
	v_rcp_f32_e32 v74, v74
	s_nop 0
	v_mul_f32_e32 v74, v81, v74
	v_mul_f32_e32 v71, v71, v74
	v_cvt_pk_bf16_f32 v74, v68, v69
	v_and_b32_e32 v68, 64, v90
	v_cmp_ne_u32_e32 vcc, 0, v68
	v_cvt_pk_bf16_f32 v75, v70, v71
	s_and_saveexec_b64 s[0:1], vcc
	s_cbranch_execz .LBB0_1222
	v_add_u32_e32 v70, s17, v232
	v_mov_b64_e32 v[68:69], s[70:71]
	v_mad_i64_i32 v[68:69], s[38:39], v70, s34, v[68:69]
	s_lshl_b32 s38, s72, 7
	s_ashr_i32 s39, s38, 31
	v_lshl_add_u64 v[68:69], s[38:39], 1, v[68:69]
	v_lshlrev_b32_e32 v146, 1, v148
	v_lshl_add_u64 v[68:69], v[68:69], 0, v[146:147]
	global_store_dwordx4 v[68:69], v[72:75], off
.LBB0_1222:
	s_or_b64 exec, exec, s[0:1]
	ds_read_b32 v86, v235
	s_waitcnt lgkmcnt(0)
	v_and_b32_e32 v68, 15, v86
	v_lshl_add_u32 v249, v68, 10, v248
	v_lshlrev_b32_e32 v146, 2, v68
	v_lshl_add_u64 v[68:69], s[68:69], 0, v[146:147]
	v_lshl_add_u64 v[72:73], v[184:185], 2, v[68:69]
	v_and_b32_e32 v68, 16, v86
	v_cmp_eq_u32_e32 vcc, 0, v68
	v_and_b32_e32 v68, 32, v86
	v_cmp_eq_u32_e64 s[0:1], 0, v68
	ds_read_b128 v[68:71], v249 offset:16
	ds_read_b128 v[252:255], v249 offset:528
	v_cndmask_b32_e64 v74, v136, 0, vcc
	v_cndmask_b32_e64 v75, v137, 0, vcc
	v_cndmask_b32_e64 v78, v158, 0, vcc
	v_cndmask_b32_e64 v79, v159, 0, vcc
	v_cndmask_b32_e64 v76, v162, 0, s[0:1]
	v_cndmask_b32_e64 v77, v163, 0, s[0:1]
	v_cndmask_b32_e64 v80, v166, 0, s[0:1]
	v_cndmask_b32_e64 v81, v167, 0, s[0:1]
	v_cndmask_b32_e64 v84, v164, 0, s[0:1]
	v_cndmask_b32_e64 v85, v165, 0, s[0:1]
	s_waitcnt lgkmcnt(0)
	v_pk_fma_f32 v[70:71], v[8:9], v[114:115], v[70:71]
	v_pk_fma_f32 v[68:69], v[6:7], v[112:113], v[68:69]
	v_pk_fma_f32 v[70:71], v[110:111], v[78:79], v[70:71]
	v_pk_fma_f32 v[68:69], v[108:109], v[74:75], v[68:69]
	v_pk_fma_f32 v[74:75], v[106:107], v[80:81], v[70:71]
	v_pk_fma_f32 v[76:77], v[104:105], v[76:77], v[68:69]
	v_mov_b64_e32 v[68:69], v[252:253]
	v_mov_b64_e32 v[70:71], v[254:255]
	v_cndmask_b32_e64 v72, v132, 0, vcc
	v_cndmask_b32_e64 v73, v133, 0, vcc
	v_cndmask_b32_e64 v78, v160, 0, s[0:1]
	v_cndmask_b32_e64 v79, v161, 0, s[0:1]
	v_cndmask_b32_e64 v80, v134, 0, vcc
	v_cndmask_b32_e64 v81, v135, 0, vcc
	s_nop 0
	v_pk_fma_f32 v[68:69], v[2:3], v[100:101], v[68:69]
	s_nop 0
	v_pk_fma_f32 v[68:69], v[96:97], v[72:73], v[68:69]
	v_exp_f32_e32 v72, v76
	v_pk_fma_f32 v[68:69], v[92:93], v[78:79], v[68:69]
	v_pk_fma_f32 v[70:71], v[4:5], v[102:103], v[70:71]
	v_add_f32_e32 v72, 1.0, v72
	v_rcp_f32_e32 v72, v72
	v_pk_fma_f32 v[70:71], v[98:99], v[80:81], v[70:71]
	v_mul_f32_e32 v72, v76, v72
	v_mul_f32_e32 v68, v68, v72
	v_exp_f32_e32 v72, v77
	v_pk_fma_f32 v[70:71], v[94:95], v[84:85], v[70:71]
	v_add_f32_e32 v72, 1.0, v72
	v_rcp_f32_e32 v72, v72
	s_nop 0
	v_mul_f32_e32 v72, v77, v72
	v_mul_f32_e32 v69, v69, v72
	v_exp_f32_e32 v72, v74
	v_cvt_pk_bf16_f32 v68, v68, v69
	s_nop 0
	v_add_f32_e32 v72, 1.0, v72
	v_rcp_f32_e32 v72, v72
	s_nop 0
	v_mul_f32_e32 v72, v74, v72
	v_mul_f32_e32 v70, v70, v72
	v_exp_f32_e32 v72, v75
	s_nop 0
	v_add_f32_e32 v72, 1.0, v72
	v_rcp_f32_e32 v72, v72
	s_nop 0
	v_mul_f32_e32 v72, v75, v72
	v_mul_f32_e32 v71, v71, v72
	v_cvt_pk_bf16_f32 v69, v70, v71
	v_and_b32_e32 v70, 64, v86
	v_cmp_ne_u32_e32 vcc, 0, v70
	s_and_saveexec_b64 s[0:1], vcc
	s_cbranch_execz .LBB0_1224
	v_add_u32_e32 v72, s17, v234
	v_mov_b64_e32 v[70:71], s[70:71]
	v_mad_i64_i32 v[70:71], s[38:39], v72, s34, v[70:71]
	s_lshl_b32 s38, s72, 7
	s_ashr_i32 s39, s38, 31
	v_lshl_add_u64 v[70:71], s[38:39], 1, v[70:71]
	v_lshlrev_b32_e32 v146, 1, v148
	v_lshl_add_u64 v[70:71], v[70:71], 0, v[146:147]
	global_store_dwordx4 v[70:71], v[66:69], off
.LBB0_1224:
	s_or_b64 exec, exec, s[0:1]
	ds_read_b32 v86, v237
	s_waitcnt lgkmcnt(0)
	v_and_b32_e32 v66, 15, v86
	v_lshl_add_u32 v249, v66, 10, v248
	v_lshlrev_b32_e32 v146, 2, v66
	v_lshl_add_u64 v[66:67], s[68:69], 0, v[146:147]
	v_lshl_add_u64 v[70:71], v[184:185], 2, v[66:67]
	v_and_b32_e32 v66, 16, v86
	v_cmp_eq_u32_e32 vcc, 0, v66
	v_and_b32_e32 v66, 32, v86
	v_cmp_eq_u32_e64 s[0:1], 0, v66
	ds_read_b128 v[66:69], v249 offset:16
	ds_read_b128 v[252:255], v249 offset:528
	v_cndmask_b32_e64 v72, v6, 0, vcc
	v_cndmask_b32_e64 v73, v7, 0, vcc
	v_cndmask_b32_e64 v76, v8, 0, vcc
	v_cndmask_b32_e64 v77, v9, 0, vcc
	v_cndmask_b32_e64 v74, v136, 0, s[0:1]
	v_cndmask_b32_e64 v75, v137, 0, s[0:1]
	v_cndmask_b32_e64 v78, v158, 0, s[0:1]
	v_cndmask_b32_e64 v79, v159, 0, s[0:1]
	v_cndmask_b32_e64 v80, v134, 0, s[0:1]
	v_cndmask_b32_e64 v81, v135, 0, s[0:1]
	s_waitcnt lgkmcnt(0)
	v_pk_fma_f32 v[68:69], v[12:13], v[114:115], v[68:69]
	v_pk_fma_f32 v[66:67], v[10:11], v[112:113], v[66:67]
	v_pk_fma_f32 v[68:69], v[110:111], v[76:77], v[68:69]
	v_pk_fma_f32 v[66:67], v[108:109], v[72:73], v[66:67]
	v_pk_fma_f32 v[72:73], v[106:107], v[78:79], v[68:69]
	v_pk_fma_f32 v[74:75], v[104:105], v[74:75], v[66:67]
	v_mov_b64_e32 v[66:67], v[252:253]
	v_mov_b64_e32 v[68:69], v[254:255]
	v_cndmask_b32_e64 v70, v2, 0, vcc
	v_cndmask_b32_e64 v71, v3, 0, vcc
	v_cndmask_b32_e64 v76, v132, 0, s[0:1]
	v_cndmask_b32_e64 v77, v133, 0, s[0:1]
	v_cndmask_b32_e64 v78, v4, 0, vcc
	v_cndmask_b32_e64 v79, v5, 0, vcc
	s_nop 0
	v_pk_fma_f32 v[66:67], v[14:15], v[100:101], v[66:67]
	s_nop 0
	v_pk_fma_f32 v[66:67], v[96:97], v[70:71], v[66:67]
	v_exp_f32_e32 v70, v74
	v_pk_fma_f32 v[66:67], v[92:93], v[76:77], v[66:67]
	v_pk_fma_f32 v[68:69], v[16:17], v[102:103], v[68:69]
	v_add_f32_e32 v70, 1.0, v70
	v_rcp_f32_e32 v70, v70
	v_pk_fma_f32 v[68:69], v[98:99], v[78:79], v[68:69]
	v_mul_f32_e32 v70, v74, v70
	v_mul_f32_e32 v66, v66, v70
	v_exp_f32_e32 v70, v75
	v_pk_fma_f32 v[68:69], v[94:95], v[80:81], v[68:69]
	v_add_f32_e32 v70, 1.0, v70
	v_rcp_f32_e32 v70, v70
	s_nop 0
	v_mul_f32_e32 v70, v75, v70
	v_mul_f32_e32 v67, v67, v70
	v_exp_f32_e32 v70, v72
	v_cvt_pk_bf16_f32 v84, v66, v67
	v_and_b32_e32 v66, 64, v86
	v_cmp_ne_u32_e32 vcc, 0, v66
	v_add_f32_e32 v70, 1.0, v70
	v_rcp_f32_e32 v70, v70
	s_nop 0
	v_mul_f32_e32 v70, v72, v70
	v_mul_f32_e32 v68, v68, v70
	v_exp_f32_e32 v70, v73
	s_nop 0
	v_add_f32_e32 v70, 1.0, v70
	v_rcp_f32_e32 v70, v70
	s_nop 0
	v_mul_f32_e32 v70, v73, v70
	v_mul_f32_e32 v69, v69, v70
	v_cvt_pk_bf16_f32 v85, v68, v69
	s_and_saveexec_b64 s[0:1], vcc
	s_cbranch_execz .LBB0_1226
	v_add_u32_e32 v68, s17, v236
	v_mov_b64_e32 v[66:67], s[70:71]
	v_mad_i64_i32 v[66:67], s[38:39], v68, s34, v[66:67]
	s_lshl_b32 s38, s72, 7
	s_ashr_i32 s39, s38, 31
	v_lshl_add_u64 v[66:67], s[38:39], 1, v[66:67]
	v_lshlrev_b32_e32 v146, 1, v148
	v_lshl_add_u64 v[66:67], v[66:67], 0, v[146:147]
	global_store_dwordx4 v[66:67], v[82:85], off

.LBB0_1231:
	s_waitcnt vmcnt(0)
	v_pk_fma_f32 v[70:71], v[212:213], v[82:83], v[90:91]
	v_pk_fma_f32 v[116:117], v[210:211], v[80:81], v[88:89]
	v_pk_fma_f32 v[70:71], v[78:79], v[68:69], v[70:71]
	s_waitcnt lgkmcnt(1)
	v_mov_b32_dpp v106, v60 row_shr:1 row_mask:0xf bank_mask:0xf
	v_mov_b32_dpp v107, v61 row_shr:1 row_mask:0xf bank_mask:0xf
	v_pk_fma_f32 v[116:117], v[76:77], v[66:67], v[116:117]
	v_pk_fma_f32 v[70:71], v[74:75], v[114:115], v[70:71]
	v_pk_fma_f32 v[114:115], v[216:217], v[98:99], v[102:103]
	s_waitcnt lgkmcnt(0)
	v_mov_b32_dpp v110, v52 row_shr:1 row_mask:0xf bank_mask:0xf
	v_mov_b32_dpp v111, v53 row_shr:1 row_mask:0xf bank_mask:0xf
	v_pk_fma_f32 v[112:113], v[72:73], v[112:113], v[116:117]
	v_pk_fma_f32 v[114:115], v[94:95], v[106:107], v[114:115]
	v_mov_b32_dpp v104, v58 row_shr:1 row_mask:0xf bank_mask:0xf
	v_pk_fma_f32 v[110:111], v[86:87], v[110:111], v[114:115]
	v_exp_f32_e32 v114, v112
	v_mov_b32_dpp v105, v59 row_shr:1 row_mask:0xf bank_mask:0xf
	v_pk_fma_f32 v[116:117], v[214:215], v[96:97], v[100:101]
	v_mov_b32_dpp v108, v50 row_shr:1 row_mask:0xf bank_mask:0xf
	v_add_f32_e32 v114, 1.0, v114
	v_rcp_f32_e32 v114, v114
	v_mov_b32_dpp v109, v51 row_shr:1 row_mask:0xf bank_mask:0xf
	v_pk_fma_f32 v[116:117], v[92:93], v[104:105], v[116:117]
	v_pk_fma_f32 v[62:63], v[62:63], v[80:81], v[88:89]
	v_pk_fma_f32 v[108:109], v[84:85], v[108:109], v[116:117]
	v_mul_f32_e32 v112, v112, v114
	v_mul_f32_e32 v108, v112, v108
	v_exp_f32_e32 v112, v113
	v_pk_fma_f32 v[58:59], v[58:59], v[96:97], v[100:101]
	v_pk_fma_f32 v[64:65], v[64:65], v[82:83], v[90:91]
	v_pk_fma_f32 v[60:61], v[60:61], v[98:99], v[102:103]
	v_add_f32_e32 v112, 1.0, v112
	v_rcp_f32_e32 v112, v112
	s_andn2_b64 vcc, exec, s[12:13]
	v_mul_f32_e32 v112, v113, v112
	v_mul_f32_e32 v109, v112, v109
	v_exp_f32_e32 v112, v70
	s_nop 0
	v_add_f32_e32 v112, 1.0, v112
	v_rcp_f32_e32 v112, v112
	s_nop 0
	v_mul_f32_e32 v70, v70, v112
	v_mul_f32_e32 v110, v70, v110
	v_exp_f32_e32 v70, v71
	s_nop 0
	v_add_f32_e32 v70, 1.0, v70
	v_rcp_f32_e32 v70, v70
	s_nop 0
	v_mul_f32_e32 v70, v71, v70
	v_mul_f32_e32 v71, v70, v111
	v_cvt_pk_bf16_f32 v70, v108, v109
	v_pk_fma_f32 v[108:109], v[204:205], v[82:83], v[90:91]
	v_cvt_pk_bf16_f32 v71, v110, v71
	v_pk_fma_f32 v[110:111], v[202:203], v[80:81], v[88:89]
	v_pk_fma_f32 v[108:109], v[212:213], v[78:79], v[108:109]
	v_pk_fma_f32 v[110:111], v[210:211], v[76:77], v[110:111]
	v_pk_fma_f32 v[68:69], v[74:75], v[68:69], v[108:109]
	v_pk_fma_f32 v[108:109], v[208:209], v[98:99], v[102:103]
	v_pk_fma_f32 v[66:67], v[72:73], v[66:67], v[110:111]
	v_pk_fma_f32 v[108:109], v[216:217], v[94:95], v[108:109]
	v_pk_fma_f32 v[110:111], v[206:207], v[96:97], v[100:101]
	v_pk_fma_f32 v[106:107], v[86:87], v[106:107], v[108:109]
	v_exp_f32_e32 v108, v66
	v_pk_fma_f32 v[110:111], v[214:215], v[92:93], v[110:111]
	v_add_f32_e32 v108, 1.0, v108
	v_rcp_f32_e32 v108, v108
	v_pk_fma_f32 v[104:105], v[84:85], v[104:105], v[110:111]
	v_mul_f32_e32 v66, v66, v108
	v_mul_f32_e32 v66, v66, v104
	v_exp_f32_e32 v104, v67
	v_pk_fma_f32 v[108:109], v[50:51], v[96:97], v[100:101]
	v_pk_fma_f32 v[50:51], v[50:51], v[92:93], v[58:59]
	v_pk_fma_f32 v[108:109], v[206:207], v[92:93], v[108:109]
	v_add_f32_e32 v104, 1.0, v104
	v_rcp_f32_e32 v104, v104
	v_pk_fma_f32 v[50:51], v[206:207], v[84:85], v[50:51]
	v_pk_fma_f32 v[108:109], v[214:215], v[84:85], v[108:109]
	v_mul_f32_e32 v67, v67, v104
	v_exp_f32_e32 v104, v68
	v_mul_f32_e32 v67, v67, v105
	v_add_f32_e32 v104, 1.0, v104
	v_rcp_f32_e32 v104, v104
	s_nop 0
	v_mul_f32_e32 v68, v68, v104
	v_mul_f32_e32 v104, v68, v106
	v_exp_f32_e32 v68, v69
	s_nop 0
	v_add_f32_e32 v68, 1.0, v68
	v_rcp_f32_e32 v68, v68
	s_nop 0
	v_mul_f32_e32 v68, v69, v68
	v_mul_f32_e32 v69, v68, v107
	v_cvt_pk_bf16_f32 v69, v104, v69
	v_pk_fma_f32 v[104:105], v[54:55], v[80:81], v[88:89]
	v_pk_fma_f32 v[54:55], v[54:55], v[76:77], v[62:63]
	v_pk_fma_f32 v[104:105], v[202:203], v[76:77], v[104:105]
	v_pk_fma_f32 v[54:55], v[202:203], v[72:73], v[54:55]
	v_pk_fma_f32 v[104:105], v[210:211], v[72:73], v[104:105]
	v_exp_f32_e32 v58, v54
	v_exp_f32_e32 v110, v104
	v_cvt_pk_bf16_f32 v68, v66, v67
	v_pk_fma_f32 v[66:67], v[56:57], v[82:83], v[90:91]
	v_add_f32_e32 v58, 1.0, v58
	v_add_f32_e32 v110, 1.0, v110
	v_rcp_f32_e32 v58, v58
	v_rcp_f32_e32 v110, v110
	v_pk_fma_f32 v[66:67], v[204:205], v[78:79], v[66:67]
	v_pk_fma_f32 v[56:57], v[56:57], v[78:79], v[64:65]
	v_mul_f32_e32 v54, v54, v58
	v_mul_f32_e32 v104, v104, v110
	v_mul_f32_e32 v50, v50, v54
	v_mul_f32_e32 v104, v108, v104
	v_exp_f32_e32 v54, v55
	v_exp_f32_e32 v108, v105
	v_pk_fma_f32 v[66:67], v[212:213], v[74:75], v[66:67]
	v_pk_fma_f32 v[56:57], v[204:205], v[74:75], v[56:57]
	v_add_f32_e32 v54, 1.0, v54
	v_add_f32_e32 v108, 1.0, v108
	v_rcp_f32_e32 v54, v54
	v_rcp_f32_e32 v108, v108
	v_pk_fma_f32 v[106:107], v[52:53], v[98:99], v[102:103]
	v_pk_fma_f32 v[52:53], v[52:53], v[94:95], v[60:61]
	v_mul_f32_e32 v54, v55, v54
	v_mul_f32_e32 v105, v105, v108
	v_mul_f32_e32 v51, v51, v54
	v_exp_f32_e32 v108, v66
	v_exp_f32_e32 v54, v56
	v_pk_fma_f32 v[106:107], v[208:209], v[94:95], v[106:107]
	v_pk_fma_f32 v[52:53], v[208:209], v[86:87], v[52:53]
	v_add_f32_e32 v108, 1.0, v108
	v_add_f32_e32 v54, 1.0, v54
	v_rcp_f32_e32 v108, v108
	v_rcp_f32_e32 v54, v54
	v_pk_fma_f32 v[106:107], v[216:217], v[86:87], v[106:107]
	v_mul_f32_e32 v105, v109, v105
	v_mul_f32_e32 v66, v66, v108
	v_mul_f32_e32 v54, v56, v54
	v_mul_f32_e32 v106, v106, v66
	v_mul_f32_e32 v52, v52, v54
	v_exp_f32_e32 v66, v67
	v_exp_f32_e32 v54, v57
	v_cvt_pk_bf16_f32 v56, v50, v51
	v_cndmask_b32_e64 v50, 0, 1, s[12:13]
	v_add_f32_e32 v66, 1.0, v66
	v_add_f32_e32 v54, 1.0, v54
	v_rcp_f32_e32 v66, v66
	v_rcp_f32_e32 v54, v54
	v_mov_b32_e32 v62, 0
	v_cmp_ne_u32_e64 s[62:63], 1, v50
	v_mul_f32_e32 v66, v67, v66
	v_mul_f32_e32 v54, v57, v54
	v_mul_f32_e32 v67, v107, v66
	v_mul_f32_e32 v53, v53, v54
	v_cvt_pk_bf16_f32 v66, v104, v105
	v_cvt_pk_bf16_f32 v67, v106, v67
	v_cvt_pk_bf16_f32 v57, v52, v53
	v_mov_b32_e32 v104, 0
	v_mov_b32_e32 v105, 0
	v_mov_b32_e32 v106, 0
	v_mov_b32_e32 v107, 0
	v_mov_b32_e32 v50, 0
	v_mov_b32_e32 v51, 0
	v_mov_b32_e32 v52, 0
	v_mov_b32_e32 v53, 0
	s_cbranch_vccnz .LBB0_1233
	ds_read_b128 v[50:53], v219 offset:3072
	ds_read_b128 v[104:107], v219 offset:2048

.LBB0_1235:
	v_pk_fma_f32 v[54:55], v[196:197], v[82:83], v[90:91]
	v_pk_fma_f32 v[108:109], v[194:195], v[80:81], v[88:89]
	v_pk_fma_f32 v[54:55], v[78:79], v[52:53], v[54:55]
	s_waitcnt lgkmcnt(1)
	v_mov_b32_dpp v60, v48 row_shr:1 row_mask:0xf bank_mask:0xf
	v_mov_b32_dpp v61, v49 row_shr:1 row_mask:0xf bank_mask:0xf
	v_pk_fma_f32 v[108:109], v[76:77], v[50:51], v[108:109]
	v_pk_fma_f32 v[54:55], v[74:75], v[106:107], v[54:55]
	v_pk_fma_f32 v[106:107], v[200:201], v[98:99], v[102:103]
	s_waitcnt lgkmcnt(0)
	v_mov_b32_dpp v64, v40 row_shr:1 row_mask:0xf bank_mask:0xf
	v_mov_b32_dpp v65, v41 row_shr:1 row_mask:0xf bank_mask:0xf
	v_pk_fma_f32 v[104:105], v[72:73], v[104:105], v[108:109]
	v_pk_fma_f32 v[106:107], v[94:95], v[60:61], v[106:107]
	v_mov_b32_dpp v58, v46 row_shr:1 row_mask:0xf bank_mask:0xf
	v_pk_fma_f32 v[64:65], v[86:87], v[64:65], v[106:107]
	v_exp_f32_e32 v106, v104
	v_mov_b32_dpp v59, v47 row_shr:1 row_mask:0xf bank_mask:0xf
	v_pk_fma_f32 v[108:109], v[198:199], v[96:97], v[100:101]
	v_mov_b32_dpp v62, v38 row_shr:1 row_mask:0xf bank_mask:0xf
	v_add_f32_e32 v106, 1.0, v106
	v_rcp_f32_e32 v106, v106
	v_mov_b32_dpp v63, v39 row_shr:1 row_mask:0xf bank_mask:0xf
	v_pk_fma_f32 v[108:109], v[92:93], v[58:59], v[108:109]
	v_pk_fma_f32 v[42:43], v[42:43], v[80:81], v[88:89]
	v_pk_fma_f32 v[62:63], v[84:85], v[62:63], v[108:109]
	v_mul_f32_e32 v104, v104, v106
	v_mul_f32_e32 v62, v104, v62
	v_exp_f32_e32 v104, v105
	v_pk_fma_f32 v[44:45], v[44:45], v[82:83], v[90:91]
	s_and_b64 vcc, exec, s[60:61]
	v_add_f32_e32 v104, 1.0, v104
	v_rcp_f32_e32 v104, v104
	s_nop 0
	v_mul_f32_e32 v104, v105, v104
	v_mul_f32_e32 v63, v104, v63
	v_exp_f32_e32 v104, v54
	v_mov_b32_e32 v105, 0
	v_add_f32_e32 v104, 1.0, v104
	v_rcp_f32_e32 v104, v104
	s_nop 0
	v_mul_f32_e32 v54, v54, v104
	v_mul_f32_e32 v64, v54, v64
	v_exp_f32_e32 v54, v55
	v_mov_b32_e32 v104, 0
	v_add_f32_e32 v54, 1.0, v54
	v_rcp_f32_e32 v54, v54
	s_nop 0
	v_mul_f32_e32 v54, v55, v54
	v_mul_f32_e32 v55, v54, v65
	v_cvt_pk_bf16_f32 v54, v62, v63
	v_pk_fma_f32 v[62:63], v[188:189], v[82:83], v[90:91]
	v_cvt_pk_bf16_f32 v55, v64, v55
	v_pk_fma_f32 v[64:65], v[186:187], v[80:81], v[88:89]
	v_pk_fma_f32 v[62:63], v[196:197], v[78:79], v[62:63]
	v_pk_fma_f32 v[64:65], v[194:195], v[76:77], v[64:65]
	v_pk_fma_f32 v[52:53], v[74:75], v[52:53], v[62:63]
	v_pk_fma_f32 v[62:63], v[192:193], v[98:99], v[102:103]
	v_pk_fma_f32 v[50:51], v[72:73], v[50:51], v[64:65]
	v_pk_fma_f32 v[62:63], v[200:201], v[94:95], v[62:63]
	v_pk_fma_f32 v[64:65], v[190:191], v[96:97], v[100:101]
	v_pk_fma_f32 v[60:61], v[86:87], v[60:61], v[62:63]
	v_exp_f32_e32 v62, v50
	v_pk_fma_f32 v[64:65], v[198:199], v[92:93], v[64:65]
	v_add_f32_e32 v62, 1.0, v62
	v_rcp_f32_e32 v62, v62
	v_pk_fma_f32 v[58:59], v[84:85], v[58:59], v[64:65]
	v_mul_f32_e32 v50, v50, v62
	v_mul_f32_e32 v50, v50, v58
	v_exp_f32_e32 v58, v51
	v_pk_fma_f32 v[62:63], v[38:39], v[96:97], v[100:101]
	v_add_f32_e32 v58, 1.0, v58
	v_rcp_f32_e32 v58, v58
	v_pk_fma_f32 v[62:63], v[190:191], v[92:93], v[62:63]
	v_mul_f32_e32 v51, v51, v58
	v_exp_f32_e32 v58, v52
	v_mul_f32_e32 v51, v51, v59
	v_pk_fma_f32 v[62:63], v[198:199], v[84:85], v[62:63]
	v_add_f32_e32 v58, 1.0, v58
	v_rcp_f32_e32 v58, v58
	s_nop 0
	v_mul_f32_e32 v52, v52, v58
	v_mul_f32_e32 v58, v52, v60
	v_exp_f32_e32 v52, v53
	s_nop 0
	v_add_f32_e32 v52, 1.0, v52
	v_rcp_f32_e32 v52, v52
	s_nop 0
	v_mul_f32_e32 v52, v53, v52
	v_mul_f32_e32 v53, v52, v61
	v_cvt_pk_bf16_f32 v53, v58, v53
	v_pk_fma_f32 v[58:59], v[34:35], v[80:81], v[88:89]
	v_pk_fma_f32 v[34:35], v[34:35], v[76:77], v[42:43]
	v_pk_fma_f32 v[42:43], v[48:49], v[98:99], v[102:103]
	v_pk_fma_f32 v[34:35], v[186:187], v[72:73], v[34:35]
	v_pk_fma_f32 v[60:61], v[40:41], v[98:99], v[102:103]
	v_pk_fma_f32 v[40:41], v[40:41], v[94:95], v[42:43]
	v_exp_f32_e32 v42, v34
	v_pk_fma_f32 v[58:59], v[186:187], v[76:77], v[58:59]
	v_cvt_pk_bf16_f32 v52, v50, v51
	v_pk_fma_f32 v[50:51], v[36:37], v[82:83], v[90:91]
	v_add_f32_e32 v42, 1.0, v42
	v_pk_fma_f32 v[58:59], v[194:195], v[72:73], v[58:59]
	v_rcp_f32_e32 v42, v42
	v_exp_f32_e32 v64, v58
	v_pk_fma_f32 v[36:37], v[36:37], v[78:79], v[44:45]
	v_pk_fma_f32 v[44:45], v[46:47], v[96:97], v[100:101]
	v_mul_f32_e32 v34, v34, v42
	v_pk_fma_f32 v[38:39], v[38:39], v[92:93], v[44:45]
	v_add_f32_e32 v64, 1.0, v64
	v_pk_fma_f32 v[38:39], v[190:191], v[84:85], v[38:39]
	v_rcp_f32_e32 v64, v64
	v_mul_f32_e32 v34, v38, v34
	v_exp_f32_e32 v38, v35
	v_mul_f32_e32 v58, v58, v64
	v_mul_f32_e32 v58, v62, v58
	v_add_f32_e32 v38, 1.0, v38
	v_rcp_f32_e32 v38, v38
	v_exp_f32_e32 v62, v59
	v_pk_fma_f32 v[36:37], v[188:189], v[74:75], v[36:37]
	v_pk_fma_f32 v[50:51], v[188:189], v[78:79], v[50:51]
	v_mul_f32_e32 v35, v35, v38
	v_exp_f32_e32 v38, v36
	v_add_f32_e32 v62, 1.0, v62
	v_rcp_f32_e32 v62, v62
	v_pk_fma_f32 v[50:51], v[196:197], v[74:75], v[50:51]
	v_add_f32_e32 v38, 1.0, v38
	v_rcp_f32_e32 v38, v38
	v_mul_f32_e32 v59, v59, v62
	v_exp_f32_e32 v62, v50
	v_mul_f32_e32 v36, v36, v38
	v_exp_f32_e32 v38, v37
	v_add_f32_e32 v62, 1.0, v62
	v_rcp_f32_e32 v62, v62
	v_pk_fma_f32 v[60:61], v[192:193], v[94:95], v[60:61]
	v_add_f32_e32 v38, 1.0, v38
	v_rcp_f32_e32 v38, v38
	v_pk_fma_f32 v[60:61], v[200:201], v[86:87], v[60:61]
	v_mul_f32_e32 v50, v50, v62
	v_mul_f32_e32 v60, v60, v50
	v_exp_f32_e32 v50, v51
	v_pk_fma_f32 v[40:41], v[192:193], v[86:87], v[40:41]
	v_mul_f32_e32 v35, v39, v35
	v_mul_f32_e32 v36, v40, v36
	v_mul_f32_e32 v37, v37, v38
	v_mul_f32_e32 v37, v41, v37
	v_cvt_pk_bf16_f32 v34, v34, v35
	v_cvt_pk_bf16_f32 v35, v36, v37
	v_or_b32_e32 v36, 4, v184
	v_ashrrev_i32_e32 v37, 31, v36
	v_add_f32_e32 v50, 1.0, v50
	v_lshlrev_b64 v[40:41], 2, v[36:37]
	v_rcp_f32_e32 v50, v50
	v_lshl_add_u64 v[42:43], s[96:97], 0, v[40:41]
	v_lshl_add_u64 v[36:37], s[4:5], 0, v[40:41]
	global_load_dwordx4 v[44:47], v[42:43], off
	v_lshl_add_u64 v[42:43], s[78:79], 0, v[40:41]
	v_lshl_add_u64 v[40:41], s[0:1], 0, v[40:41]
	global_load_dwordx4 v[36:39], v[36:37], off
	v_mul_f32_e32 v59, v63, v59
	global_load_dwordx4 v[78:81], v[40:41], off
	v_or_b32_e32 v40, 0x84, v184
	v_ashrrev_i32_e32 v41, 31, v40
	v_mul_f32_e32 v50, v51, v50
	v_lshlrev_b64 v[48:49], 2, v[40:41]
	v_mul_f32_e32 v51, v61, v50
	v_cvt_pk_bf16_f32 v50, v58, v59
	v_lshl_add_u64 v[58:59], s[96:97], 0, v[48:49]
	v_cvt_pk_bf16_f32 v51, v60, v51
	global_load_dwordx4 v[60:63], v[42:43], off
	global_load_dwordx4 v[74:77], v[58:59], off
	v_lshl_add_u64 v[40:41], s[4:5], 0, v[48:49]
	v_lshl_add_u64 v[58:59], s[78:79], 0, v[48:49]
	v_lshl_add_u64 v[48:49], s[0:1], 0, v[48:49]
	global_load_dwordx4 v[40:43], v[40:41], off
	v_mov_b32_e32 v98, 0
	global_load_dwordx4 v[82:85], v[58:59], off
	global_load_dwordx4 v[86:89], v[48:49], off
	v_mov_b32_e32 v102, 0
	v_mov_b32_e32 v103, 0
	v_mov_b32_e32 v90, 0
	v_mov_b32_e32 v91, 0
	v_mov_b32_e32 v92, 0
	v_mov_b32_e32 v93, 0
	s_cbranch_vccnz .LBB0_1237
	ds_read_b128 v[90:93], v221 offset:16
	ds_read_b128 v[102:105], v222 offset:16

.LBB0_1239:
	s_waitcnt vmcnt(4)
	v_pk_fma_f32 v[58:59], v[178:179], v[60:61], v[78:79]
	s_waitcnt lgkmcnt(1)
	v_mov_b32_dpp v94, v26 row_shr:1 row_mask:0xf bank_mask:0xf
	v_mov_b32_dpp v95, v27 row_shr:1 row_mask:0xf bank_mask:0xf
	v_pk_fma_f32 v[58:59], v[44:45], v[90:91], v[58:59]
	s_waitcnt vmcnt(0)
	v_pk_fma_f32 v[72:73], v[176:177], v[82:83], v[86:87]
	s_waitcnt lgkmcnt(0)
	v_mov_b32_dpp v98, v18 row_shr:1 row_mask:0xf bank_mask:0xf
	v_mov_b32_dpp v99, v19 row_shr:1 row_mask:0xf bank_mask:0xf
	v_pk_fma_f32 v[58:59], v[36:37], v[102:103], v[58:59]
	v_pk_fma_f32 v[72:73], v[74:75], v[94:95], v[72:73]
	v_pk_fma_f32 v[48:49], v[182:183], v[62:63], v[80:81]
	v_pk_fma_f32 v[72:73], v[40:41], v[98:99], v[72:73]
	v_exp_f32_e32 v98, v58
	v_pk_fma_f32 v[48:49], v[46:47], v[92:93], v[48:49]
	v_mov_b32_dpp v96, v28 row_shr:1 row_mask:0xf bank_mask:0xf
	v_pk_fma_f32 v[48:49], v[38:39], v[104:105], v[48:49]
	v_add_f32_e32 v98, 1.0, v98
	v_rcp_f32_e32 v98, v98
	v_mov_b32_dpp v97, v29 row_shr:1 row_mask:0xf bank_mask:0xf
	v_pk_fma_f32 v[64:65], v[180:181], v[84:85], v[88:89]
	v_mov_b32_dpp v100, v20 row_shr:1 row_mask:0xf bank_mask:0xf
	v_mul_f32_e32 v58, v58, v98
	v_mul_f32_e32 v58, v58, v72
	v_exp_f32_e32 v72, v59
	v_mov_b32_dpp v101, v21 row_shr:1 row_mask:0xf bank_mask:0xf
	v_pk_fma_f32 v[64:65], v[76:77], v[96:97], v[64:65]
	v_lshlrev_b32_e32 v146, 1, v148
	v_add_f32_e32 v72, 1.0, v72
	v_rcp_f32_e32 v72, v72
	v_pk_fma_f32 v[64:65], v[42:43], v[100:101], v[64:65]
	v_mul_f32_e32 v59, v59, v72
	v_exp_f32_e32 v72, v48
	v_mul_f32_e32 v59, v59, v73
	v_add_f32_e32 v72, 1.0, v72
	v_rcp_f32_e32 v72, v72
	s_nop 0
	v_mul_f32_e32 v48, v48, v72
	v_mul_f32_e32 v48, v48, v64
	v_exp_f32_e32 v64, v49
	v_cvt_pk_bf16_f32 v72, v58, v59
	s_nop 0
	v_add_f32_e32 v64, 1.0, v64
	v_rcp_f32_e32 v64, v64
	s_nop 0
	v_mul_f32_e32 v49, v49, v64
	v_mul_f32_e32 v49, v49, v65
	v_cvt_pk_bf16_f32 v73, v48, v49
	s_and_saveexec_b64 s[0:1], s[46:47]
	s_cbranch_execz .LBB0_1241
	v_add_u32_e32 v58, s17, v220
	v_mov_b64_e32 v[48:49], s[70:71]
	v_mad_i64_i32 v[48:49], s[38:39], v58, s34, v[48:49]
	s_lshl_b32 s38, s72, 7
	s_ashr_i32 s39, s38, 31
	v_lshl_add_u64 v[48:49], s[38:39], 1, v[48:49]
	v_lshl_add_u64 v[48:49], v[48:49], 0, v[146:147]
	global_store_dwordx4 v[48:49], v[70:73], off
.LBB0_1241:
	s_or_b64 exec, exec, s[0:1]
	v_pk_fma_f32 v[58:59], v[172:173], v[60:61], v[78:79]
	v_pk_fma_f32 v[70:71], v[168:169], v[82:83], v[86:87]
	v_pk_fma_f32 v[58:59], v[178:179], v[44:45], v[58:59]
	v_pk_fma_f32 v[70:71], v[176:177], v[74:75], v[70:71]
	v_pk_fma_f32 v[58:59], v[36:37], v[90:91], v[58:59]
	v_pk_fma_f32 v[70:71], v[40:41], v[94:95], v[70:71]
	v_exp_f32_e32 v72, v58
	v_pk_fma_f32 v[48:49], v[174:175], v[62:63], v[80:81]
	v_pk_fma_f32 v[64:65], v[170:171], v[84:85], v[88:89]
	v_pk_fma_f32 v[48:49], v[182:183], v[46:47], v[48:49]
	v_add_f32_e32 v72, 1.0, v72
	v_rcp_f32_e32 v72, v72
	v_pk_fma_f32 v[48:49], v[38:39], v[92:93], v[48:49]
	v_pk_fma_f32 v[64:65], v[180:181], v[76:77], v[64:65]
	v_mul_f32_e32 v58, v58, v72
	v_mul_f32_e32 v58, v58, v70
	v_exp_f32_e32 v70, v59
	v_pk_fma_f32 v[64:65], v[42:43], v[96:97], v[64:65]
	v_add_f32_e32 v70, 1.0, v70
	v_rcp_f32_e32 v70, v70
	s_nop 0
	v_mul_f32_e32 v59, v59, v70
	v_exp_f32_e32 v70, v48
	v_mul_f32_e32 v59, v59, v71
	v_add_f32_e32 v70, 1.0, v70
	v_rcp_f32_e32 v70, v70
	s_nop 0
	v_mul_f32_e32 v48, v48, v70
	v_mul_f32_e32 v48, v48, v64
	v_exp_f32_e32 v64, v49
	v_cvt_pk_bf16_f32 v70, v58, v59
	s_nop 0
	v_add_f32_e32 v64, 1.0, v64
	v_rcp_f32_e32 v64, v64
	s_nop 0
	v_mul_f32_e32 v49, v49, v64
	v_mul_f32_e32 v49, v49, v65
	v_cvt_pk_bf16_f32 v71, v48, v49
	s_and_saveexec_b64 s[0:1], s[48:49]
	s_cbranch_execz .LBB0_1243
	v_add_u32_e32 v58, s17, v224
	v_mov_b64_e32 v[48:49], s[70:71]
	v_mad_i64_i32 v[48:49], s[38:39], v58, s34, v[48:49]
	s_lshl_b32 s38, s72, 7
	s_ashr_i32 s39, s38, 31
	v_lshl_add_u64 v[48:49], s[38:39], 1, v[48:49]
	v_lshl_add_u64 v[48:49], v[48:49], 0, v[146:147]
	global_store_dwordx4 v[48:49], v[68:71], off
.LBB0_1243:
	s_or_b64 exec, exec, s[0:1]
	v_pk_fma_f32 v[58:59], v[22:23], v[60:61], v[78:79]
	v_pk_fma_f32 v[68:69], v[18:19], v[82:83], v[86:87]
	v_pk_fma_f32 v[58:59], v[172:173], v[44:45], v[58:59]
	v_pk_fma_f32 v[68:69], v[168:169], v[74:75], v[68:69]
	v_pk_fma_f32 v[58:59], v[178:179], v[36:37], v[58:59]
	v_pk_fma_f32 v[68:69], v[176:177], v[40:41], v[68:69]
	v_exp_f32_e32 v70, v58
	v_pk_fma_f32 v[48:49], v[24:25], v[62:63], v[80:81]
	v_pk_fma_f32 v[64:65], v[20:21], v[84:85], v[88:89]
	v_pk_fma_f32 v[48:49], v[174:175], v[46:47], v[48:49]
	v_add_f32_e32 v70, 1.0, v70
	v_rcp_f32_e32 v70, v70
	v_pk_fma_f32 v[48:49], v[182:183], v[38:39], v[48:49]
	v_pk_fma_f32 v[64:65], v[170:171], v[76:77], v[64:65]
	s_andn2_b64 vcc, exec, s[14:15]
	v_mul_f32_e32 v58, v58, v70
	v_mul_f32_e32 v58, v68, v58
	v_exp_f32_e32 v68, v59
	v_pk_fma_f32 v[64:65], v[180:181], v[42:43], v[64:65]
	v_add_f32_e32 v68, 1.0, v68
	v_rcp_f32_e32 v68, v68
	s_nop 0
	v_mul_f32_e32 v59, v59, v68
	v_exp_f32_e32 v68, v48
	v_mul_f32_e32 v59, v69, v59
	v_add_f32_e32 v68, 1.0, v68
	v_rcp_f32_e32 v68, v68
	s_nop 0
	v_mul_f32_e32 v48, v48, v68
	v_mul_f32_e32 v48, v64, v48
	v_exp_f32_e32 v64, v49
	v_cvt_pk_bf16_f32 v68, v58, v59
	s_nop 0
	v_add_f32_e32 v64, 1.0, v64
	v_rcp_f32_e32 v64, v64
	s_nop 0
	v_mul_f32_e32 v49, v49, v64
	v_mul_f32_e32 v49, v65, v49
	v_cvt_pk_bf16_f32 v69, v48, v49
	v_cndmask_b32_e64 v48, 0, 1, s[14:15]
	v_cmp_ne_u32_e64 s[0:1], 1, v48
	s_cbranch_vccnz .LBB0_1245
	v_add_u32_e32 v58, s17, v226
	v_mov_b64_e32 v[48:49], s[70:71]
	v_mad_i64_i32 v[48:49], s[38:39], v58, s34, v[48:49]
	s_lshl_b32 s38, s72, 7
	s_ashr_i32 s39, s38, 31
	v_lshl_add_u64 v[48:49], s[38:39], 1, v[48:49]
	v_lshl_add_u64 v[48:49], v[48:49], 0, v[146:147]
	global_store_dwordx4 v[48:49], v[66:69], off
.LBB0_1245:
	v_pk_fma_f32 v[30:31], v[30:31], v[60:61], v[78:79]
	v_pk_fma_f32 v[26:27], v[26:27], v[82:83], v[86:87]
	v_pk_fma_f32 v[22:23], v[22:23], v[44:45], v[30:31]
	v_pk_fma_f32 v[18:19], v[18:19], v[74:75], v[26:27]
	v_pk_fma_f32 v[22:23], v[172:173], v[36:37], v[22:23]
	v_pk_fma_f32 v[32:33], v[32:33], v[62:63], v[80:81]
	v_exp_f32_e32 v30, v22
	v_exp_f32_e32 v27, v23
	v_pk_fma_f32 v[24:25], v[24:25], v[46:47], v[32:33]
	v_add_f32_e32 v26, 1.0, v30
	v_rcp_f32_e32 v26, v26
	v_pk_fma_f32 v[24:25], v[174:175], v[38:39], v[24:25]
	v_pk_fma_f32 v[18:19], v[168:169], v[40:41], v[18:19]
	v_pk_fma_f32 v[28:29], v[28:29], v[84:85], v[88:89]
	v_mul_f32_e32 v22, v22, v26
	v_mul_f32_e32 v18, v18, v22
	v_add_f32_e32 v22, 1.0, v27
	v_rcp_f32_e32 v22, v22
	v_exp_f32_e32 v26, v24
	v_exp_f32_e32 v27, v25
	v_mul_f32_e32 v22, v23, v22
	v_add_f32_e32 v23, 1.0, v26
	v_rcp_f32_e32 v23, v23
	v_add_f32_e32 v26, 1.0, v27
	v_rcp_f32_e32 v26, v26
	v_pk_fma_f32 v[20:21], v[20:21], v[76:77], v[28:29]
	v_mul_f32_e32 v19, v19, v22
	v_pk_fma_f32 v[20:21], v[170:171], v[42:43], v[20:21]
	v_mul_f32_e32 v22, v24, v23
	v_mul_f32_e32 v20, v20, v22
	v_mul_f32_e32 v22, v25, v26
	s_and_b64 vcc, exec, s[0:1]
	v_mul_f32_e32 v21, v21, v22
	v_cvt_pk_bf16_f32 v58, v18, v19
	v_cvt_pk_bf16_f32 v59, v20, v21
	s_cbranch_vccnz .LBB0_1247
	v_add_u32_e32 v20, s17, v228
	v_mov_b64_e32 v[18:19], s[70:71]
	v_mad_i64_i32 v[18:19], s[0:1], v20, s34, v[18:19]
	s_lshl_b32 s0, s72, 7
	s_ashr_i32 s1, s0, 31
	v_lshl_add_u64 v[18:19], s[0:1], 1, v[18:19]
	v_lshl_add_u64 v[18:19], v[18:19], 0, v[146:147]
	global_store_dwordx4 v[18:19], v[56:59], off

.LBB0_1251:
	v_pk_fma_f32 v[48:49], v[166:167], v[62:63], v[80:81]
	v_pk_fma_f32 v[56:57], v[162:163], v[60:61], v[78:79]
	v_pk_fma_f32 v[48:49], v[46:47], v[20:21], v[48:49]
	s_waitcnt lgkmcnt(1)
	v_mov_b32_dpp v24, v16 row_shr:1 row_mask:0xf bank_mask:0xf
	v_mov_b32_dpp v25, v17 row_shr:1 row_mask:0xf bank_mask:0xf
	v_pk_fma_f32 v[56:57], v[44:45], v[18:19], v[56:57]
	v_pk_fma_f32 v[32:33], v[38:39], v[32:33], v[48:49]
	v_pk_fma_f32 v[48:49], v[164:165], v[84:85], v[88:89]
	s_waitcnt lgkmcnt(0)
	v_mov_b32_dpp v28, v4 row_shr:1 row_mask:0xf bank_mask:0xf
	v_mov_b32_dpp v29, v5 row_shr:1 row_mask:0xf bank_mask:0xf
	v_pk_fma_f32 v[30:31], v[36:37], v[30:31], v[56:57]
	v_pk_fma_f32 v[48:49], v[76:77], v[24:25], v[48:49]
	v_mov_b32_dpp v22, v14 row_shr:1 row_mask:0xf bank_mask:0xf
	v_pk_fma_f32 v[28:29], v[42:43], v[28:29], v[48:49]
	v_exp_f32_e32 v48, v30
	v_mov_b32_dpp v23, v15 row_shr:1 row_mask:0xf bank_mask:0xf
	v_pk_fma_f32 v[56:57], v[160:161], v[82:83], v[86:87]
	v_mov_b32_dpp v26, v2 row_shr:1 row_mask:0xf bank_mask:0xf
	v_add_f32_e32 v48, 1.0, v48
	v_rcp_f32_e32 v48, v48
	v_mov_b32_dpp v27, v3 row_shr:1 row_mask:0xf bank_mask:0xf
	v_pk_fma_f32 v[56:57], v[74:75], v[22:23], v[56:57]
	v_mul_f32_e32 v30, v30, v48
	v_pk_fma_f32 v[26:27], v[40:41], v[26:27], v[56:57]
	s_nop 0
	v_mul_f32_e32 v26, v30, v26
	v_exp_f32_e32 v30, v31
	s_nop 0
	v_add_f32_e32 v30, 1.0, v30
	v_rcp_f32_e32 v30, v30
	s_nop 0
	v_mul_f32_e32 v30, v31, v30
	v_mul_f32_e32 v27, v30, v27
	v_exp_f32_e32 v30, v32
	v_cvt_pk_bf16_f32 v56, v26, v27
	s_nop 0
	v_add_f32_e32 v30, 1.0, v30
	v_rcp_f32_e32 v30, v30
	s_nop 0
	v_mul_f32_e32 v30, v32, v30
	v_mul_f32_e32 v28, v30, v28
	v_exp_f32_e32 v30, v33
	s_nop 0
	v_add_f32_e32 v30, 1.0, v30
	v_rcp_f32_e32 v30, v30
	s_nop 0
	v_mul_f32_e32 v30, v33, v30
	v_mul_f32_e32 v29, v30, v29
	v_cvt_pk_bf16_f32 v57, v28, v29
	s_and_saveexec_b64 s[0:1], s[50:51]
	s_cbranch_execz .LBB0_1253
	v_add_u32_e32 v28, s17, v230
	v_mov_b64_e32 v[26:27], s[70:71]
	v_mad_i64_i32 v[26:27], s[38:39], v28, s34, v[26:27]
	s_lshl_b32 s38, s72, 7
	s_ashr_i32 s39, s38, 31
	v_lshl_add_u64 v[26:27], s[38:39], 1, v[26:27]
	v_lshl_add_u64 v[26:27], v[26:27], 0, v[146:147]
	global_store_dwordx4 v[26:27], v[54:57], off
.LBB0_1253:
	s_or_b64 exec, exec, s[0:1]
	v_pk_fma_f32 v[26:27], v[158:159], v[62:63], v[80:81]
	v_pk_fma_f32 v[28:29], v[136:137], v[60:61], v[78:79]
	v_pk_fma_f32 v[26:27], v[166:167], v[46:47], v[26:27]
	v_pk_fma_f32 v[28:29], v[162:163], v[44:45], v[28:29]
	v_pk_fma_f32 v[20:21], v[38:39], v[20:21], v[26:27]
	v_pk_fma_f32 v[26:27], v[134:135], v[84:85], v[88:89]
	v_pk_fma_f32 v[18:19], v[36:37], v[18:19], v[28:29]
	v_pk_fma_f32 v[26:27], v[164:165], v[76:77], v[26:27]
	v_pk_fma_f32 v[28:29], v[132:133], v[82:83], v[86:87]
	v_pk_fma_f32 v[24:25], v[42:43], v[24:25], v[26:27]
	v_exp_f32_e32 v26, v18
	v_pk_fma_f32 v[28:29], v[160:161], v[74:75], v[28:29]
	v_add_f32_e32 v26, 1.0, v26
	v_rcp_f32_e32 v26, v26
	v_pk_fma_f32 v[22:23], v[40:41], v[22:23], v[28:29]
	v_mul_f32_e32 v18, v18, v26
	v_mul_f32_e32 v18, v18, v22
	v_exp_f32_e32 v22, v19
	s_nop 0
	v_add_f32_e32 v22, 1.0, v22
	v_rcp_f32_e32 v22, v22
	s_nop 0
	v_mul_f32_e32 v19, v19, v22
	v_exp_f32_e32 v22, v20
	v_mul_f32_e32 v19, v19, v23
	v_cvt_pk_bf16_f32 v54, v18, v19
	v_add_f32_e32 v22, 1.0, v22
	v_rcp_f32_e32 v22, v22
	s_nop 0
	v_mul_f32_e32 v20, v20, v22
	v_exp_f32_e32 v22, v21
	v_mul_f32_e32 v20, v20, v24
	v_add_f32_e32 v22, 1.0, v22
	v_rcp_f32_e32 v22, v22
	s_nop 0
	v_mul_f32_e32 v21, v21, v22
	v_mul_f32_e32 v21, v21, v25
	v_cvt_pk_bf16_f32 v55, v20, v21
	s_and_saveexec_b64 s[0:1], s[52:53]
	s_cbranch_execz .LBB0_1255
	v_add_u32_e32 v20, s17, v232
	v_mov_b64_e32 v[18:19], s[70:71]
	v_mad_i64_i32 v[18:19], s[38:39], v20, s34, v[18:19]
	s_lshl_b32 s38, s72, 7
	s_ashr_i32 s39, s38, 31
	v_lshl_add_u64 v[18:19], s[38:39], 1, v[18:19]
	v_lshl_add_u64 v[18:19], v[18:19], 0, v[146:147]
	global_store_dwordx4 v[18:19], v[52:55], off
.LBB0_1255:
	s_or_b64 exec, exec, s[0:1]
	v_pk_fma_f32 v[20:21], v[6:7], v[60:61], v[78:79]
	v_pk_fma_f32 v[24:25], v[2:3], v[82:83], v[86:87]
	v_pk_fma_f32 v[20:21], v[136:137], v[44:45], v[20:21]
	v_pk_fma_f32 v[24:25], v[132:133], v[74:75], v[24:25]
	v_pk_fma_f32 v[20:21], v[162:163], v[36:37], v[20:21]
	v_pk_fma_f32 v[24:25], v[160:161], v[40:41], v[24:25]
	v_exp_f32_e32 v26, v20
	v_pk_fma_f32 v[18:19], v[8:9], v[62:63], v[80:81]
	v_pk_fma_f32 v[22:23], v[4:5], v[84:85], v[88:89]
	v_pk_fma_f32 v[18:19], v[158:159], v[46:47], v[18:19]
	v_add_f32_e32 v26, 1.0, v26
	v_rcp_f32_e32 v26, v26
	v_pk_fma_f32 v[18:19], v[166:167], v[38:39], v[18:19]
	v_pk_fma_f32 v[22:23], v[134:135], v[76:77], v[22:23]
	v_mul_f32_e32 v20, v20, v26
	v_mul_f32_e32 v20, v24, v20
	v_exp_f32_e32 v24, v21
	v_pk_fma_f32 v[22:23], v[164:165], v[42:43], v[22:23]
	v_add_f32_e32 v24, 1.0, v24
	v_rcp_f32_e32 v24, v24
	s_nop 0
	v_mul_f32_e32 v21, v21, v24
	v_exp_f32_e32 v24, v18
	v_mul_f32_e32 v21, v25, v21
	v_cvt_pk_bf16_f32 v52, v20, v21
	v_add_f32_e32 v24, 1.0, v24
	v_rcp_f32_e32 v24, v24
	s_nop 0
	v_mul_f32_e32 v18, v18, v24
	v_mul_f32_e32 v18, v22, v18
	v_exp_f32_e32 v22, v19
	s_nop 0
	v_add_f32_e32 v22, 1.0, v22
	v_rcp_f32_e32 v22, v22
	s_nop 0
	v_mul_f32_e32 v19, v19, v22
	v_mul_f32_e32 v19, v23, v19
	v_cvt_pk_bf16_f32 v53, v18, v19
	s_and_saveexec_b64 s[0:1], s[54:55]
	s_cbranch_execz .LBB0_1257
	v_add_u32_e32 v20, s17, v234
	v_mov_b64_e32 v[18:19], s[70:71]
	v_mad_i64_i32 v[18:19], s[38:39], v20, s34, v[18:19]
	s_lshl_b32 s38, s72, 7
	s_ashr_i32 s39, s38, 31
	v_lshl_add_u64 v[18:19], s[38:39], 1, v[18:19]
	v_lshl_add_u64 v[18:19], v[18:19], 0, v[146:147]
	global_store_dwordx4 v[18:19], v[50:53], off
.LBB0_1257:
	s_or_b64 exec, exec, s[0:1]
	v_pk_fma_f32 v[10:11], v[10:11], v[60:61], v[78:79]
	v_pk_fma_f32 v[12:13], v[12:13], v[62:63], v[80:81]
	v_pk_fma_f32 v[6:7], v[6:7], v[44:45], v[10:11]
	v_pk_fma_f32 v[8:9], v[8:9], v[46:47], v[12:13]
	v_pk_fma_f32 v[6:7], v[136:137], v[36:37], v[6:7]
	v_pk_fma_f32 v[12:13], v[14:15], v[82:83], v[86:87]
	v_exp_f32_e32 v14, v6
	v_pk_fma_f32 v[10:11], v[16:17], v[84:85], v[88:89]
	v_pk_fma_f32 v[2:3], v[2:3], v[74:75], v[12:13]
	v_pk_fma_f32 v[4:5], v[4:5], v[76:77], v[10:11]
	v_add_f32_e32 v10, 1.0, v14
	v_rcp_f32_e32 v10, v10
	v_exp_f32_e32 v11, v7
	v_pk_fma_f32 v[8:9], v[158:159], v[38:39], v[8:9]
	v_pk_fma_f32 v[2:3], v[132:133], v[40:41], v[2:3]
	v_mul_f32_e32 v6, v6, v10
	v_mul_f32_e32 v2, v2, v6
	v_add_f32_e32 v6, 1.0, v11
	v_rcp_f32_e32 v6, v6
	v_exp_f32_e32 v10, v8
	v_exp_f32_e32 v11, v9
	v_mul_f32_e32 v6, v7, v6
	v_add_f32_e32 v7, 1.0, v10
	v_rcp_f32_e32 v7, v7
	v_add_f32_e32 v10, 1.0, v11
	v_rcp_f32_e32 v10, v10
	v_pk_fma_f32 v[4:5], v[134:135], v[42:43], v[4:5]
	v_mul_f32_e32 v3, v3, v6
	v_mul_f32_e32 v6, v8, v7
	v_mul_f32_e32 v4, v4, v6
	v_mul_f32_e32 v6, v9, v10
	v_mul_f32_e32 v5, v5, v6
	v_cvt_pk_bf16_f32 v36, v2, v3
	v_cvt_pk_bf16_f32 v37, v4, v5
	s_and_saveexec_b64 s[0:1], s[56:57]
	s_cbranch_execz .LBB0_1259
	v_add_u32_e32 v4, s17, v236
	v_mov_b64_e32 v[2:3], s[70:71]
	v_mad_i64_i32 v[2:3], s[38:39], v4, s34, v[2:3]
	s_lshl_b32 s38, s72, 7
	s_ashr_i32 s39, s38, 31
	v_lshl_add_u64 v[2:3], s[38:39], 1, v[2:3]
	v_lshl_add_u64 v[2:3], v[2:3], 0, v[146:147]
	global_store_dwordx4 v[2:3], v[34:37], off
